# v15 + Gray-code MFMA order with m as the inner non-k index (shares the weight-side fragment srcA on 6 of 7 non-chain transitions instead of the activation-side srcB)
# speedup vs baseline: 1.0029x; 1.0029x over previous
.LBB0_364:
	s_add_u32 s20, s18, 0xfff80080
	s_addc_u32 s21, s19, -1
	s_add_i32 s30, 0, 0x10000
	s_cmp_eq_u32 s29, 28
	s_cselect_b32 s23, s4, s21
	s_cselect_b32 s22, s24, s20
	s_cselect_b32 s21, s25, s28
	s_cselect_b32 s20, s26, s27
	s_add_i32 s42, 0, 0x14000
	v_add_u32_e32 v142, s30, v204
	v_add_u32_e32 v166, s42, v204
	ds_read_b128 v[130:133], v142
	ds_read_b128 v[134:137], v142 offset:1024
	ds_read_b128 v[138:141], v142 offset:2048
	ds_read_b128 v[142:145], v142 offset:3072
	ds_read_b128 v[146:149], v166
	ds_read_b128 v[150:153], v166 offset:1024
	ds_read_b128 v[154:157], v166 offset:2048
	ds_read_b128 v[166:169], v166 offset:3072
	v_lshl_add_u64 v[202:203], s[18:19], 0, v[162:163]
	s_add_i32 m0, s87, 0xc000
	ds_read_b128 v[170:173], v205
	ds_read_b128 v[174:177], v205 offset:1024
	ds_read_b128 v[178:181], v205 offset:2048
	ds_read_b128 v[182:185], v205 offset:3072
	ds_read_b128 v[186:189], v205 offset:4096
	ds_read_b128 v[190:193], v205 offset:5120
	ds_read_b128 v[206:209], v205 offset:6144
	ds_read_b128 v[210:213], v205 offset:7168
	global_load_lds_dwordx4 v[202:203], off
	v_lshl_add_u64 v[202:203], s[18:19], 0, v[164:165]
	s_add_i32 m0, s87, 0xe000
	s_nop 0
	global_load_lds_dwordx4 v[202:203], off
	s_waitcnt vmcnt(8)
	s_waitcnt lgkmcnt(0)
	s_setprio 1
	s_barrier
	v_mfma_f32_16x16x32_bf16 v[126:129], v[130:133], v[170:173], v[126:129]
	v_mfma_f32_16x16x32_bf16 v[126:129], v[134:137], v[174:177], v[126:129]
	v_mfma_f32_16x16x32_bf16 v[110:113], v[134:137], v[182:185], v[110:113]
	v_mfma_f32_16x16x32_bf16 v[110:113], v[130:133], v[178:181], v[110:113]
	v_mfma_f32_16x16x32_bf16 v[94:97], v[130:133], v[186:189], v[94:97]
	v_mfma_f32_16x16x32_bf16 v[94:97], v[134:137], v[190:193], v[94:97]
	v_mfma_f32_16x16x32_bf16 v[78:81], v[134:137], v[210:213], v[78:81]
	v_mfma_f32_16x16x32_bf16 v[78:81], v[130:133], v[206:209], v[78:81]
	v_mfma_f32_16x16x32_bf16 v[74:77], v[138:141], v[206:209], v[74:77]
	v_mfma_f32_16x16x32_bf16 v[74:77], v[142:145], v[210:213], v[74:77]
	v_mfma_f32_16x16x32_bf16 v[90:93], v[142:145], v[190:193], v[90:93]
	v_mfma_f32_16x16x32_bf16 v[90:93], v[138:141], v[186:189], v[90:93]
	v_mfma_f32_16x16x32_bf16 v[106:109], v[138:141], v[178:181], v[106:109]
	v_mfma_f32_16x16x32_bf16 v[106:109], v[142:145], v[182:185], v[106:109]
	v_mfma_f32_16x16x32_bf16 v[122:125], v[142:145], v[174:177], v[122:125]
	v_mfma_f32_16x16x32_bf16 v[122:125], v[138:141], v[170:173], v[122:125]
	v_mfma_f32_16x16x32_bf16 v[118:121], v[146:149], v[170:173], v[118:121]
	v_mfma_f32_16x16x32_bf16 v[118:121], v[150:153], v[174:177], v[118:121]
	v_mfma_f32_16x16x32_bf16 v[102:105], v[150:153], v[182:185], v[102:105]
	v_mfma_f32_16x16x32_bf16 v[102:105], v[146:149], v[178:181], v[102:105]
	v_mfma_f32_16x16x32_bf16 v[86:89], v[146:149], v[186:189], v[86:89]
	v_mfma_f32_16x16x32_bf16 v[86:89], v[150:153], v[190:193], v[86:89]
	v_mfma_f32_16x16x32_bf16 v[70:73], v[150:153], v[210:213], v[70:73]
	v_mfma_f32_16x16x32_bf16 v[70:73], v[146:149], v[206:209], v[70:73]
	v_mfma_f32_16x16x32_bf16 v[66:69], v[154:157], v[206:209], v[66:69]
	v_mfma_f32_16x16x32_bf16 v[66:69], v[166:169], v[210:213], v[66:69]
	v_mfma_f32_16x16x32_bf16 v[82:85], v[166:169], v[190:193], v[82:85]
	v_mfma_f32_16x16x32_bf16 v[82:85], v[154:157], v[186:189], v[82:85]
	v_mfma_f32_16x16x32_bf16 v[98:101], v[154:157], v[178:181], v[98:101]
	v_mfma_f32_16x16x32_bf16 v[98:101], v[166:169], v[182:185], v[98:101]
	v_mfma_f32_16x16x32_bf16 v[114:117], v[166:169], v[174:177], v[114:117]
	v_mfma_f32_16x16x32_bf16 v[114:117], v[154:157], v[170:173], v[114:117]
	s_barrier
	s_setprio 0
	s_add_i32 s30, s30, s39
	v_lshl_add_u64 v[202:203], s[20:21], 0, v[158:159]
	s_mov_b32 m0, s30
	ds_read_b128 v[170:173], v205 offset:16384
	ds_read_b128 v[174:177], v205 offset:17408
	ds_read_b128 v[178:181], v205 offset:18432
	ds_read_b128 v[182:185], v205 offset:19456
	ds_read_b128 v[186:189], v205 offset:20480
	ds_read_b128 v[190:193], v205 offset:21504
	ds_read_b128 v[206:209], v205 offset:22528
	ds_read_b128 v[210:213], v205 offset:23552
	global_load_lds_dwordx4 v[202:203], off
	s_add_i32 m0, s30, 0x2000
	s_add_u32 s30, s20, 0x80000
	v_lshl_add_u64 v[214:215], s[20:21], 0, v[160:161]
	s_addc_u32 s31, s21, 0
	s_add_i32 s42, s42, s39
	global_load_lds_dwordx4 v[214:215], off
	v_lshl_add_u64 v[216:217], s[30:31], 0, v[158:159]
	s_mov_b32 m0, s42
	v_lshl_add_u64 v[228:229], s[22:23], 0, v[160:161]
	global_load_lds_dwordx4 v[216:217], off
	v_lshl_add_u64 v[216:217], s[30:31], 0, v[160:161]
	s_add_i32 m0, s42, 0x2000
	s_nop 0
	global_load_lds_dwordx4 v[216:217], off
	v_lshl_add_u64 v[216:217], s[22:23], 0, v[158:159]
	s_mov_b32 m0, s87
	s_nop 0
	global_load_lds_dwordx4 v[216:217], off
	s_mov_b32 m0, s92
	s_nop 0
	global_load_lds_dwordx4 v[228:229], off
	s_waitcnt vmcnt(8)
	s_waitcnt lgkmcnt(0)
	s_setprio 1
	s_barrier
	v_mfma_f32_16x16x32_bf16 v[62:65], v[130:133], v[170:173], v[62:65]
	v_mfma_f32_16x16x32_bf16 v[62:65], v[134:137], v[174:177], v[62:65]
	v_mfma_f32_16x16x32_bf16 v[46:49], v[134:137], v[182:185], v[46:49]
	v_mfma_f32_16x16x32_bf16 v[46:49], v[130:133], v[178:181], v[46:49]
	v_mfma_f32_16x16x32_bf16 v[30:33], v[130:133], v[186:189], v[30:33]
	v_mfma_f32_16x16x32_bf16 v[30:33], v[134:137], v[190:193], v[30:33]
	v_mfma_f32_16x16x32_bf16 v[14:17], v[134:137], v[210:213], v[14:17]
	v_mfma_f32_16x16x32_bf16 v[14:17], v[130:133], v[206:209], v[14:17]
	v_mfma_f32_16x16x32_bf16 v[10:13], v[138:141], v[206:209], v[10:13]
	v_mfma_f32_16x16x32_bf16 v[10:13], v[142:145], v[210:213], v[10:13]
	v_mfma_f32_16x16x32_bf16 v[26:29], v[142:145], v[190:193], v[26:29]
	v_mfma_f32_16x16x32_bf16 v[26:29], v[138:141], v[186:189], v[26:29]
	v_mfma_f32_16x16x32_bf16 v[42:45], v[138:141], v[178:181], v[42:45]
	v_mfma_f32_16x16x32_bf16 v[42:45], v[142:145], v[182:185], v[42:45]
	v_mfma_f32_16x16x32_bf16 v[58:61], v[142:145], v[174:177], v[58:61]
	v_mfma_f32_16x16x32_bf16 v[58:61], v[138:141], v[170:173], v[58:61]
	v_mfma_f32_16x16x32_bf16 v[54:57], v[146:149], v[170:173], v[54:57]
	v_mfma_f32_16x16x32_bf16 v[54:57], v[150:153], v[174:177], v[54:57]
	v_mfma_f32_16x16x32_bf16 v[38:41], v[150:153], v[182:185], v[38:41]
	v_mfma_f32_16x16x32_bf16 v[38:41], v[146:149], v[178:181], v[38:41]
	v_mfma_f32_16x16x32_bf16 v[22:25], v[146:149], v[186:189], v[22:25]
	v_mfma_f32_16x16x32_bf16 v[22:25], v[150:153], v[190:193], v[22:25]
	v_mfma_f32_16x16x32_bf16 v[6:9], v[150:153], v[210:213], v[6:9]
	v_mfma_f32_16x16x32_bf16 v[6:9], v[146:149], v[206:209], v[6:9]
	v_mfma_f32_16x16x32_bf16 v[2:5], v[154:157], v[206:209], v[2:5]
	v_mfma_f32_16x16x32_bf16 v[2:5], v[166:169], v[210:213], v[2:5]
	v_mfma_f32_16x16x32_bf16 v[18:21], v[166:169], v[190:193], v[18:21]
	v_mfma_f32_16x16x32_bf16 v[18:21], v[154:157], v[186:189], v[18:21]
	v_mfma_f32_16x16x32_bf16 v[34:37], v[154:157], v[178:181], v[34:37]
	v_mfma_f32_16x16x32_bf16 v[34:37], v[166:169], v[182:185], v[34:37]
	v_mfma_f32_16x16x32_bf16 v[50:53], v[166:169], v[174:177], v[50:53]
	v_mfma_f32_16x16x32_bf16 v[50:53], v[154:157], v[170:173], v[50:53]
	s_barrier
	s_setprio 0
	s_add_i32 s30, 0, 0x18000
	s_add_i32 s31, 0, 0x1c000
	v_add_u32_e32 v142, s30, v204
	v_add_u32_e32 v166, s31, v204
	ds_read_b128 v[130:133], v142
	ds_read_b128 v[134:137], v142 offset:1024
	ds_read_b128 v[138:141], v142 offset:2048
	ds_read_b128 v[142:145], v142 offset:3072
	ds_read_b128 v[146:149], v166
	ds_read_b128 v[150:153], v166 offset:1024
	ds_read_b128 v[154:157], v166 offset:2048
	ds_read_b128 v[166:169], v166 offset:3072
	s_add_u32 s22, s22, 0x80000
	s_addc_u32 s23, s23, 0
	s_mov_b32 m0, s8
	v_lshl_add_u64 v[230:231], s[22:23], 0, v[158:159]
	ds_read_b128 v[170:173], v205 offset:32768
	ds_read_b128 v[174:177], v205 offset:33792
	ds_read_b128 v[178:181], v205 offset:34816
	ds_read_b128 v[182:185], v205 offset:35840
	ds_read_b128 v[186:189], v205 offset:36864
	ds_read_b128 v[190:193], v205 offset:37888
	ds_read_b128 v[206:209], v205 offset:38912
	ds_read_b128 v[210:213], v205 offset:39936
	global_load_lds_dwordx4 v[230:231], off
	v_lshl_add_u64 v[230:231], s[22:23], 0, v[160:161]
	s_mov_b32 m0, s9
	s_nop 0
	global_load_lds_dwordx4 v[230:231], off
	s_waitcnt vmcnt(8)
	s_waitcnt lgkmcnt(0)
	s_setprio 1
	s_barrier
	v_mfma_f32_16x16x32_bf16 v[126:129], v[130:133], v[170:173], v[126:129]
	v_mfma_f32_16x16x32_bf16 v[126:129], v[134:137], v[174:177], v[126:129]
	v_mfma_f32_16x16x32_bf16 v[110:113], v[134:137], v[182:185], v[110:113]
	v_mfma_f32_16x16x32_bf16 v[110:113], v[130:133], v[178:181], v[110:113]
	v_mfma_f32_16x16x32_bf16 v[94:97], v[130:133], v[186:189], v[94:97]
	v_mfma_f32_16x16x32_bf16 v[94:97], v[134:137], v[190:193], v[94:97]
	v_mfma_f32_16x16x32_bf16 v[78:81], v[134:137], v[210:213], v[78:81]
	v_mfma_f32_16x16x32_bf16 v[78:81], v[130:133], v[206:209], v[78:81]
	v_mfma_f32_16x16x32_bf16 v[74:77], v[138:141], v[206:209], v[74:77]
	v_mfma_f32_16x16x32_bf16 v[74:77], v[142:145], v[210:213], v[74:77]
	v_mfma_f32_16x16x32_bf16 v[90:93], v[142:145], v[190:193], v[90:93]
	v_mfma_f32_16x16x32_bf16 v[90:93], v[138:141], v[186:189], v[90:93]
	v_mfma_f32_16x16x32_bf16 v[106:109], v[138:141], v[178:181], v[106:109]
	v_mfma_f32_16x16x32_bf16 v[106:109], v[142:145], v[182:185], v[106:109]
	v_mfma_f32_16x16x32_bf16 v[122:125], v[142:145], v[174:177], v[122:125]
	v_mfma_f32_16x16x32_bf16 v[122:125], v[138:141], v[170:173], v[122:125]
	v_mfma_f32_16x16x32_bf16 v[118:121], v[146:149], v[170:173], v[118:121]
	v_mfma_f32_16x16x32_bf16 v[118:121], v[150:153], v[174:177], v[118:121]
	v_mfma_f32_16x16x32_bf16 v[102:105], v[150:153], v[182:185], v[102:105]
	v_mfma_f32_16x16x32_bf16 v[102:105], v[146:149], v[178:181], v[102:105]
	v_mfma_f32_16x16x32_bf16 v[86:89], v[146:149], v[186:189], v[86:89]
	v_mfma_f32_16x16x32_bf16 v[86:89], v[150:153], v[190:193], v[86:89]
	v_mfma_f32_16x16x32_bf16 v[70:73], v[150:153], v[210:213], v[70:73]
	v_mfma_f32_16x16x32_bf16 v[70:73], v[146:149], v[206:209], v[70:73]
	v_mfma_f32_16x16x32_bf16 v[66:69], v[154:157], v[206:209], v[66:69]
	v_mfma_f32_16x16x32_bf16 v[66:69], v[166:169], v[210:213], v[66:69]
	v_mfma_f32_16x16x32_bf16 v[82:85], v[166:169], v[190:193], v[82:85]
	v_mfma_f32_16x16x32_bf16 v[82:85], v[154:157], v[186:189], v[82:85]
	v_mfma_f32_16x16x32_bf16 v[98:101], v[154:157], v[178:181], v[98:101]
	v_mfma_f32_16x16x32_bf16 v[98:101], v[166:169], v[182:185], v[98:101]
	v_mfma_f32_16x16x32_bf16 v[114:117], v[166:169], v[174:177], v[114:117]
	v_mfma_f32_16x16x32_bf16 v[114:117], v[154:157], v[170:173], v[114:117]
	s_barrier
	s_setprio 0
	s_add_i32 s22, s30, s39
	v_lshl_add_u64 v[202:203], v[202:203], 0, s[10:11]
	s_mov_b32 m0, s22
	ds_read_b128 v[170:173], v205 offset:49152
	ds_read_b128 v[174:177], v205 offset:50176
	ds_read_b128 v[178:181], v205 offset:51200
	ds_read_b128 v[182:185], v205 offset:52224
	ds_read_b128 v[186:189], v205 offset:53248
	ds_read_b128 v[190:193], v205 offset:54272
	ds_read_b128 v[206:209], v205 offset:55296
	ds_read_b128 v[210:213], v205 offset:56320
	global_load_lds_dwordx4 v[202:203], off
	s_add_i32 m0, s22, 0x2000
	s_add_u32 s20, s20, 0x80080
	v_lshl_add_u64 v[202:203], v[214:215], 0, s[10:11]
	s_addc_u32 s21, s21, 0
	s_add_i32 s22, s31, s39
	global_load_lds_dwordx4 v[202:203], off
	v_lshl_add_u64 v[202:203], s[20:21], 0, v[158:159]
	s_mov_b32 m0, s22
	s_nop 0
	global_load_lds_dwordx4 v[202:203], off
	v_lshl_add_u64 v[202:203], s[20:21], 0, v[160:161]
	s_add_i32 m0, s22, 0x2000
	s_nop 0
	global_load_lds_dwordx4 v[202:203], off
	v_lshl_add_u64 v[202:203], v[216:217], 0, s[10:11]
	s_mov_b32 m0, s56
	s_nop 0
	global_load_lds_dwordx4 v[202:203], off
	v_lshl_add_u64 v[202:203], v[228:229], 0, s[10:11]
	s_mov_b32 m0, s57
	s_nop 0
	global_load_lds_dwordx4 v[202:203], off
	s_waitcnt vmcnt(8)
	s_waitcnt lgkmcnt(0)
	s_setprio 1
	s_barrier
	v_mfma_f32_16x16x32_bf16 v[62:65], v[130:133], v[170:173], v[62:65]
	v_mfma_f32_16x16x32_bf16 v[62:65], v[134:137], v[174:177], v[62:65]
	v_mfma_f32_16x16x32_bf16 v[46:49], v[134:137], v[182:185], v[46:49]
	v_mfma_f32_16x16x32_bf16 v[46:49], v[130:133], v[178:181], v[46:49]
	v_mfma_f32_16x16x32_bf16 v[30:33], v[130:133], v[186:189], v[30:33]
	v_mfma_f32_16x16x32_bf16 v[30:33], v[134:137], v[190:193], v[30:33]
	v_mfma_f32_16x16x32_bf16 v[14:17], v[134:137], v[210:213], v[14:17]
	v_mfma_f32_16x16x32_bf16 v[14:17], v[130:133], v[206:209], v[14:17]
	v_mfma_f32_16x16x32_bf16 v[10:13], v[138:141], v[206:209], v[10:13]
	v_mfma_f32_16x16x32_bf16 v[10:13], v[142:145], v[210:213], v[10:13]
	v_mfma_f32_16x16x32_bf16 v[26:29], v[142:145], v[190:193], v[26:29]
	v_mfma_f32_16x16x32_bf16 v[26:29], v[138:141], v[186:189], v[26:29]
	v_mfma_f32_16x16x32_bf16 v[42:45], v[138:141], v[178:181], v[42:45]
	v_mfma_f32_16x16x32_bf16 v[42:45], v[142:145], v[182:185], v[42:45]
	v_mfma_f32_16x16x32_bf16 v[58:61], v[142:145], v[174:177], v[58:61]
	v_mfma_f32_16x16x32_bf16 v[58:61], v[138:141], v[170:173], v[58:61]
	v_mfma_f32_16x16x32_bf16 v[54:57], v[146:149], v[170:173], v[54:57]
	v_mfma_f32_16x16x32_bf16 v[54:57], v[150:153], v[174:177], v[54:57]
	v_mfma_f32_16x16x32_bf16 v[38:41], v[150:153], v[182:185], v[38:41]
	v_mfma_f32_16x16x32_bf16 v[38:41], v[146:149], v[178:181], v[38:41]
	v_mfma_f32_16x16x32_bf16 v[22:25], v[146:149], v[186:189], v[22:25]
	v_mfma_f32_16x16x32_bf16 v[22:25], v[150:153], v[190:193], v[22:25]
	v_mfma_f32_16x16x32_bf16 v[6:9], v[150:153], v[210:213], v[6:9]
	v_mfma_f32_16x16x32_bf16 v[6:9], v[146:149], v[206:209], v[6:9]
	v_mfma_f32_16x16x32_bf16 v[2:5], v[154:157], v[206:209], v[2:5]
	v_mfma_f32_16x16x32_bf16 v[2:5], v[166:169], v[210:213], v[2:5]
	v_mfma_f32_16x16x32_bf16 v[18:21], v[166:169], v[190:193], v[18:21]
	v_mfma_f32_16x16x32_bf16 v[18:21], v[154:157], v[186:189], v[18:21]
	v_mfma_f32_16x16x32_bf16 v[34:37], v[154:157], v[178:181], v[34:37]
	v_mfma_f32_16x16x32_bf16 v[34:37], v[166:169], v[182:185], v[34:37]
	v_mfma_f32_16x16x32_bf16 v[50:53], v[166:169], v[174:177], v[50:53]
	v_mfma_f32_16x16x32_bf16 v[50:53], v[154:157], v[170:173], v[50:53]
	s_barrier
	s_setprio 0
	s_add_i32 s29, s29, 2
	s_add_u32 s18, s18, 0x100
	s_addc_u32 s19, s19, 0
	s_add_u32 s27, s27, 0x100
	s_addc_u32 s28, s28, 0
	s_cmp_gt_u32 s29, 29
	s_cbranch_scc0 .LBB0_364
	s_and_b64 vcc, exec, s[58:59]
	s_cbranch_vccz .LBB0_367
	s_barrier

.LBB0_986:
	s_add_u32 s24, s22, 0x100
	s_addc_u32 s25, s23, 0
	s_add_i32 s62, 0, 0x10000
	s_cmp_eq_u32 s61, 28
	s_cselect_b32 s29, s17, s25
	s_cselect_b32 s28, s58, s24
	v_add_u32_e32 v138, s62, v140
	s_cselect_b32 s27, s19, s60
	s_cselect_b32 s26, s18, s59
	s_add_i32 s63, 0, 0x14000
	ds_read_b128 v[142:145], v138
	ds_read_b128 v[146:149], v138 offset:1024
	ds_read_b128 v[150:153], v138 offset:2048
	ds_read_b128 v[154:157], v138 offset:3072
	v_add_u32_e32 v138, s63, v140
	ds_read_b128 v[158:161], v138
	ds_read_b128 v[162:165], v138 offset:1024
	ds_read_b128 v[166:169], v138 offset:2048
	ds_read_b128 v[170:173], v138 offset:3072
	v_lshl_add_u64 v[138:139], s[22:23], 0, v[134:135]
	s_add_i32 m0, s47, 0xc000
	ds_read_b128 v[174:177], v141
	ds_read_b128 v[178:181], v141 offset:1024
	ds_read_b128 v[182:185], v141 offset:2048
	ds_read_b128 v[186:189], v141 offset:3072
	ds_read_b128 v[190:193], v141 offset:4096
	ds_read_b128 v[202:205], v141 offset:5120
	ds_read_b128 v[206:209], v141 offset:6144
	ds_read_b128 v[210:213], v141 offset:7168
	global_load_lds_dwordx4 v[138:139], off
	v_lshl_add_u64 v[138:139], s[22:23], 0, v[136:137]
	s_add_i32 m0, s47, 0xe000
	s_nop 0
	global_load_lds_dwordx4 v[138:139], off
	s_waitcnt vmcnt(8)
	s_waitcnt lgkmcnt(0)
	s_setprio 1
	s_barrier
	v_mfma_f32_16x16x32_bf16 v[126:129], v[142:145], v[174:177], v[126:129]
	v_mfma_f32_16x16x32_bf16 v[126:129], v[146:149], v[178:181], v[126:129]
	v_mfma_f32_16x16x32_bf16 v[118:121], v[146:149], v[186:189], v[118:121]
	v_mfma_f32_16x16x32_bf16 v[118:121], v[142:145], v[182:185], v[118:121]
	v_mfma_f32_16x16x32_bf16 v[102:105], v[142:145], v[190:193], v[102:105]
	v_mfma_f32_16x16x32_bf16 v[102:105], v[146:149], v[202:205], v[102:105]
	v_mfma_f32_16x16x32_bf16 v[86:89], v[146:149], v[210:213], v[86:89]
	v_mfma_f32_16x16x32_bf16 v[86:89], v[142:145], v[206:209], v[86:89]
	v_mfma_f32_16x16x32_bf16 v[78:81], v[150:153], v[206:209], v[78:81]
	v_mfma_f32_16x16x32_bf16 v[78:81], v[154:157], v[210:213], v[78:81]
	v_mfma_f32_16x16x32_bf16 v[94:97], v[154:157], v[202:205], v[94:97]
	v_mfma_f32_16x16x32_bf16 v[94:97], v[150:153], v[190:193], v[94:97]
	v_mfma_f32_16x16x32_bf16 v[110:113], v[150:153], v[182:185], v[110:113]
	v_mfma_f32_16x16x32_bf16 v[110:113], v[154:157], v[186:189], v[110:113]
	v_mfma_f32_16x16x32_bf16 v[122:125], v[154:157], v[178:181], v[122:125]
	v_mfma_f32_16x16x32_bf16 v[122:125], v[150:153], v[174:177], v[122:125]
	v_mfma_f32_16x16x32_bf16 v[114:117], v[158:161], v[174:177], v[114:117]
	v_mfma_f32_16x16x32_bf16 v[114:117], v[162:165], v[178:181], v[114:117]
	v_mfma_f32_16x16x32_bf16 v[98:101], v[162:165], v[186:189], v[98:101]
	v_mfma_f32_16x16x32_bf16 v[98:101], v[158:161], v[182:185], v[98:101]
	v_mfma_f32_16x16x32_bf16 v[82:85], v[158:161], v[190:193], v[82:85]
	v_mfma_f32_16x16x32_bf16 v[82:85], v[162:165], v[202:205], v[82:85]
	v_mfma_f32_16x16x32_bf16 v[70:73], v[162:165], v[210:213], v[70:73]
	v_mfma_f32_16x16x32_bf16 v[70:73], v[158:161], v[206:209], v[70:73]
	v_mfma_f32_16x16x32_bf16 v[66:69], v[166:169], v[206:209], v[66:69]
	v_mfma_f32_16x16x32_bf16 v[66:69], v[170:173], v[210:213], v[66:69]
	v_mfma_f32_16x16x32_bf16 v[74:77], v[170:173], v[202:205], v[74:77]
	v_mfma_f32_16x16x32_bf16 v[74:77], v[166:169], v[190:193], v[74:77]
	v_mfma_f32_16x16x32_bf16 v[90:93], v[166:169], v[182:185], v[90:93]
	v_mfma_f32_16x16x32_bf16 v[90:93], v[170:173], v[186:189], v[90:93]
	v_mfma_f32_16x16x32_bf16 v[106:109], v[170:173], v[178:181], v[106:109]
	v_mfma_f32_16x16x32_bf16 v[106:109], v[166:169], v[174:177], v[106:109]
	s_barrier
	s_setprio 0
	s_add_i32 s22, s62, s36
	v_lshl_add_u64 v[138:139], s[26:27], 0, v[132:133]
	s_mov_b32 m0, s22
	ds_read_b128 v[174:177], v141 offset:16384
	ds_read_b128 v[178:181], v141 offset:17408
	ds_read_b128 v[182:185], v141 offset:18432
	ds_read_b128 v[186:189], v141 offset:19456
	ds_read_b128 v[190:193], v141 offset:20480
	ds_read_b128 v[202:205], v141 offset:21504
	ds_read_b128 v[206:209], v141 offset:22528
	ds_read_b128 v[210:213], v141 offset:23552
	global_load_lds_dwordx4 v[138:139], off
	s_add_i32 m0, s22, 0x2000
	s_add_u32 s22, s26, 0x80000
	v_lshl_add_u64 v[214:215], s[26:27], 0, v[130:131]
	s_addc_u32 s23, s27, 0
	s_add_i32 s62, s63, s36
	global_load_lds_dwordx4 v[214:215], off
	v_lshl_add_u64 v[216:217], s[22:23], 0, v[132:133]
	s_mov_b32 m0, s62
	v_lshl_add_u64 v[228:229], s[28:29], 0, v[130:131]
	global_load_lds_dwordx4 v[216:217], off
	v_lshl_add_u64 v[216:217], s[22:23], 0, v[130:131]
	s_add_i32 m0, s62, 0x2000
	s_nop 0
	global_load_lds_dwordx4 v[216:217], off
	v_lshl_add_u64 v[216:217], s[28:29], 0, v[132:133]
	s_mov_b32 m0, s47
	s_nop 0
	global_load_lds_dwordx4 v[216:217], off
	s_mov_b32 m0, s48
	s_nop 0
	global_load_lds_dwordx4 v[228:229], off
	s_waitcnt vmcnt(8)
	s_waitcnt lgkmcnt(0)
	s_setprio 1
	s_barrier
	v_mfma_f32_16x16x32_bf16 v[62:65], v[142:145], v[174:177], v[62:65]
	v_mfma_f32_16x16x32_bf16 v[62:65], v[146:149], v[178:181], v[62:65]
	v_mfma_f32_16x16x32_bf16 v[54:57], v[146:149], v[186:189], v[54:57]
	v_mfma_f32_16x16x32_bf16 v[54:57], v[142:145], v[182:185], v[54:57]
	v_mfma_f32_16x16x32_bf16 v[38:41], v[142:145], v[190:193], v[38:41]
	v_mfma_f32_16x16x32_bf16 v[38:41], v[146:149], v[202:205], v[38:41]
	v_mfma_f32_16x16x32_bf16 v[22:25], v[146:149], v[210:213], v[22:25]
	v_mfma_f32_16x16x32_bf16 v[22:25], v[142:145], v[206:209], v[22:25]
	v_mfma_f32_16x16x32_bf16 v[14:17], v[150:153], v[206:209], v[14:17]
	v_mfma_f32_16x16x32_bf16 v[14:17], v[154:157], v[210:213], v[14:17]
	v_mfma_f32_16x16x32_bf16 v[30:33], v[154:157], v[202:205], v[30:33]
	v_mfma_f32_16x16x32_bf16 v[30:33], v[150:153], v[190:193], v[30:33]
	v_mfma_f32_16x16x32_bf16 v[46:49], v[150:153], v[182:185], v[46:49]
	v_mfma_f32_16x16x32_bf16 v[46:49], v[154:157], v[186:189], v[46:49]
	v_mfma_f32_16x16x32_bf16 v[58:61], v[154:157], v[178:181], v[58:61]
	v_mfma_f32_16x16x32_bf16 v[58:61], v[150:153], v[174:177], v[58:61]
	v_mfma_f32_16x16x32_bf16 v[50:53], v[158:161], v[174:177], v[50:53]
	v_mfma_f32_16x16x32_bf16 v[50:53], v[162:165], v[178:181], v[50:53]
	v_mfma_f32_16x16x32_bf16 v[34:37], v[162:165], v[186:189], v[34:37]
	v_mfma_f32_16x16x32_bf16 v[34:37], v[158:161], v[182:185], v[34:37]
	v_mfma_f32_16x16x32_bf16 v[18:21], v[158:161], v[190:193], v[18:21]
	v_mfma_f32_16x16x32_bf16 v[18:21], v[162:165], v[202:205], v[18:21]
	v_mfma_f32_16x16x32_bf16 v[6:9], v[162:165], v[210:213], v[6:9]
	v_mfma_f32_16x16x32_bf16 v[6:9], v[158:161], v[206:209], v[6:9]
	v_mfma_f32_16x16x32_bf16 v[2:5], v[166:169], v[206:209], v[2:5]
	v_mfma_f32_16x16x32_bf16 v[2:5], v[170:173], v[210:213], v[2:5]
	v_mfma_f32_16x16x32_bf16 v[10:13], v[170:173], v[202:205], v[10:13]
	v_mfma_f32_16x16x32_bf16 v[10:13], v[166:169], v[190:193], v[10:13]
	v_mfma_f32_16x16x32_bf16 v[26:29], v[166:169], v[182:185], v[26:29]
	v_mfma_f32_16x16x32_bf16 v[26:29], v[170:173], v[186:189], v[26:29]
	v_mfma_f32_16x16x32_bf16 v[42:45], v[170:173], v[178:181], v[42:45]
	v_mfma_f32_16x16x32_bf16 v[42:45], v[166:169], v[174:177], v[42:45]
	s_barrier
	s_setprio 0
	s_add_i32 s62, 0, 0x18000
	s_add_i32 s63, 0, 0x1c000
	v_add_u32_e32 v154, s62, v140
	v_add_u32_e32 v170, s63, v140
	ds_read_b128 v[142:145], v154
	ds_read_b128 v[146:149], v154 offset:1024
	ds_read_b128 v[150:153], v154 offset:2048
	ds_read_b128 v[154:157], v154 offset:3072
	ds_read_b128 v[158:161], v170
	ds_read_b128 v[162:165], v170 offset:1024
	ds_read_b128 v[166:169], v170 offset:2048
	ds_read_b128 v[170:173], v170 offset:3072
	s_add_u32 s22, s28, 0x80000
	s_addc_u32 s23, s29, 0
	s_mov_b32 m0, s49
	v_lshl_add_u64 v[230:231], s[22:23], 0, v[132:133]
	ds_read_b128 v[174:177], v141 offset:32768
	ds_read_b128 v[178:181], v141 offset:33792
	ds_read_b128 v[182:185], v141 offset:34816
	ds_read_b128 v[186:189], v141 offset:35840
	ds_read_b128 v[190:193], v141 offset:36864
	ds_read_b128 v[202:205], v141 offset:37888
	ds_read_b128 v[206:209], v141 offset:38912
	ds_read_b128 v[210:213], v141 offset:39936
	global_load_lds_dwordx4 v[230:231], off
	v_lshl_add_u64 v[230:231], s[22:23], 0, v[130:131]
	s_mov_b32 m0, s50
	s_nop 0
	global_load_lds_dwordx4 v[230:231], off
	s_waitcnt vmcnt(8)
	s_waitcnt lgkmcnt(0)
	s_setprio 1
	s_barrier
	v_mfma_f32_16x16x32_bf16 v[126:129], v[142:145], v[174:177], v[126:129]
	v_mfma_f32_16x16x32_bf16 v[126:129], v[146:149], v[178:181], v[126:129]
	v_mfma_f32_16x16x32_bf16 v[118:121], v[146:149], v[186:189], v[118:121]
	v_mfma_f32_16x16x32_bf16 v[118:121], v[142:145], v[182:185], v[118:121]
	v_mfma_f32_16x16x32_bf16 v[102:105], v[142:145], v[190:193], v[102:105]
	v_mfma_f32_16x16x32_bf16 v[102:105], v[146:149], v[202:205], v[102:105]
	v_mfma_f32_16x16x32_bf16 v[86:89], v[146:149], v[210:213], v[86:89]
	v_mfma_f32_16x16x32_bf16 v[86:89], v[142:145], v[206:209], v[86:89]
	v_mfma_f32_16x16x32_bf16 v[78:81], v[150:153], v[206:209], v[78:81]
	v_mfma_f32_16x16x32_bf16 v[78:81], v[154:157], v[210:213], v[78:81]
	v_mfma_f32_16x16x32_bf16 v[94:97], v[154:157], v[202:205], v[94:97]
	v_mfma_f32_16x16x32_bf16 v[94:97], v[150:153], v[190:193], v[94:97]
	v_mfma_f32_16x16x32_bf16 v[110:113], v[150:153], v[182:185], v[110:113]
	v_mfma_f32_16x16x32_bf16 v[110:113], v[154:157], v[186:189], v[110:113]
	v_mfma_f32_16x16x32_bf16 v[122:125], v[154:157], v[178:181], v[122:125]
	v_mfma_f32_16x16x32_bf16 v[122:125], v[150:153], v[174:177], v[122:125]
	v_mfma_f32_16x16x32_bf16 v[114:117], v[158:161], v[174:177], v[114:117]
	v_mfma_f32_16x16x32_bf16 v[114:117], v[162:165], v[178:181], v[114:117]
	v_mfma_f32_16x16x32_bf16 v[98:101], v[162:165], v[186:189], v[98:101]
	v_mfma_f32_16x16x32_bf16 v[98:101], v[158:161], v[182:185], v[98:101]
	v_mfma_f32_16x16x32_bf16 v[82:85], v[158:161], v[190:193], v[82:85]
	v_mfma_f32_16x16x32_bf16 v[82:85], v[162:165], v[202:205], v[82:85]
	v_mfma_f32_16x16x32_bf16 v[70:73], v[162:165], v[210:213], v[70:73]
	v_mfma_f32_16x16x32_bf16 v[70:73], v[158:161], v[206:209], v[70:73]
	v_mfma_f32_16x16x32_bf16 v[66:69], v[166:169], v[206:209], v[66:69]
	v_mfma_f32_16x16x32_bf16 v[66:69], v[170:173], v[210:213], v[66:69]
	v_mfma_f32_16x16x32_bf16 v[74:77], v[170:173], v[202:205], v[74:77]
	v_mfma_f32_16x16x32_bf16 v[74:77], v[166:169], v[190:193], v[74:77]
	v_mfma_f32_16x16x32_bf16 v[90:93], v[166:169], v[182:185], v[90:93]
	v_mfma_f32_16x16x32_bf16 v[90:93], v[170:173], v[186:189], v[90:93]
	v_mfma_f32_16x16x32_bf16 v[106:109], v[170:173], v[178:181], v[106:109]
	v_mfma_f32_16x16x32_bf16 v[106:109], v[166:169], v[174:177], v[106:109]
	s_barrier
	s_setprio 0
	s_add_i32 s22, s62, s36
	v_lshl_add_u64 v[138:139], v[138:139], 0, s[10:11]
	s_mov_b32 m0, s22
	ds_read_b128 v[174:177], v141 offset:49152
	ds_read_b128 v[178:181], v141 offset:50176
	ds_read_b128 v[182:185], v141 offset:51200
	ds_read_b128 v[186:189], v141 offset:52224
	ds_read_b128 v[190:193], v141 offset:53248
	ds_read_b128 v[202:205], v141 offset:54272
	ds_read_b128 v[206:209], v141 offset:55296
	ds_read_b128 v[210:213], v141 offset:56320
	global_load_lds_dwordx4 v[138:139], off
	s_add_i32 m0, s22, 0x2000
	s_add_u32 s22, s26, 0x80080
	v_lshl_add_u64 v[138:139], v[214:215], 0, s[10:11]
	s_addc_u32 s23, s27, 0
	s_add_i32 s26, s63, s36
	global_load_lds_dwordx4 v[138:139], off
	v_lshl_add_u64 v[138:139], s[22:23], 0, v[132:133]
	s_mov_b32 m0, s26
	s_nop 0
	global_load_lds_dwordx4 v[138:139], off
	v_lshl_add_u64 v[138:139], s[22:23], 0, v[130:131]
	s_add_i32 m0, s26, 0x2000
	s_nop 0
	global_load_lds_dwordx4 v[138:139], off
	v_lshl_add_u64 v[138:139], v[216:217], 0, s[10:11]
	s_mov_b32 m0, s51
	s_nop 0
	global_load_lds_dwordx4 v[138:139], off
	v_lshl_add_u64 v[138:139], v[228:229], 0, s[10:11]
	s_mov_b32 m0, s52
	s_nop 0
	global_load_lds_dwordx4 v[138:139], off
	s_waitcnt vmcnt(8)
	s_waitcnt lgkmcnt(0)
	s_setprio 1
	s_barrier
	v_mfma_f32_16x16x32_bf16 v[62:65], v[142:145], v[174:177], v[62:65]
	v_mfma_f32_16x16x32_bf16 v[62:65], v[146:149], v[178:181], v[62:65]
	v_mfma_f32_16x16x32_bf16 v[54:57], v[146:149], v[186:189], v[54:57]
	v_mfma_f32_16x16x32_bf16 v[54:57], v[142:145], v[182:185], v[54:57]
	v_mfma_f32_16x16x32_bf16 v[38:41], v[142:145], v[190:193], v[38:41]
	v_mfma_f32_16x16x32_bf16 v[38:41], v[146:149], v[202:205], v[38:41]
	v_mfma_f32_16x16x32_bf16 v[22:25], v[146:149], v[210:213], v[22:25]
	v_mfma_f32_16x16x32_bf16 v[22:25], v[142:145], v[206:209], v[22:25]
	v_mfma_f32_16x16x32_bf16 v[14:17], v[150:153], v[206:209], v[14:17]
	v_mfma_f32_16x16x32_bf16 v[14:17], v[154:157], v[210:213], v[14:17]
	v_mfma_f32_16x16x32_bf16 v[30:33], v[154:157], v[202:205], v[30:33]
	v_mfma_f32_16x16x32_bf16 v[30:33], v[150:153], v[190:193], v[30:33]
	v_mfma_f32_16x16x32_bf16 v[46:49], v[150:153], v[182:185], v[46:49]
	v_mfma_f32_16x16x32_bf16 v[46:49], v[154:157], v[186:189], v[46:49]
	v_mfma_f32_16x16x32_bf16 v[58:61], v[154:157], v[178:181], v[58:61]
	v_mfma_f32_16x16x32_bf16 v[58:61], v[150:153], v[174:177], v[58:61]
	v_mfma_f32_16x16x32_bf16 v[50:53], v[158:161], v[174:177], v[50:53]
	v_mfma_f32_16x16x32_bf16 v[50:53], v[162:165], v[178:181], v[50:53]
	v_mfma_f32_16x16x32_bf16 v[34:37], v[162:165], v[186:189], v[34:37]
	v_mfma_f32_16x16x32_bf16 v[34:37], v[158:161], v[182:185], v[34:37]
	v_mfma_f32_16x16x32_bf16 v[18:21], v[158:161], v[190:193], v[18:21]
	v_mfma_f32_16x16x32_bf16 v[18:21], v[162:165], v[202:205], v[18:21]
	v_mfma_f32_16x16x32_bf16 v[6:9], v[162:165], v[210:213], v[6:9]
	v_mfma_f32_16x16x32_bf16 v[6:9], v[158:161], v[206:209], v[6:9]
	v_mfma_f32_16x16x32_bf16 v[2:5], v[166:169], v[206:209], v[2:5]
	v_mfma_f32_16x16x32_bf16 v[2:5], v[170:173], v[210:213], v[2:5]
	v_mfma_f32_16x16x32_bf16 v[10:13], v[170:173], v[202:205], v[10:13]
	v_mfma_f32_16x16x32_bf16 v[10:13], v[166:169], v[190:193], v[10:13]
	v_mfma_f32_16x16x32_bf16 v[26:29], v[166:169], v[182:185], v[26:29]
	v_mfma_f32_16x16x32_bf16 v[26:29], v[170:173], v[186:189], v[26:29]
	v_mfma_f32_16x16x32_bf16 v[42:45], v[170:173], v[178:181], v[42:45]
	v_mfma_f32_16x16x32_bf16 v[42:45], v[166:169], v[174:177], v[42:45]
	s_barrier
	s_setprio 0
	s_add_i32 s61, s61, 2
	s_add_u32 s59, s59, 0x100
	s_addc_u32 s60, s60, 0
	s_cmp_gt_u32 s61, 29
	s_mov_b64 s[22:23], s[24:25]
	s_cbranch_scc0 .LBB0_986
	s_and_b64 vcc, exec, s[14:15]
	s_cbranch_vccz .LBB0_989
	s_barrier

.LBB0_1002:
	s_add_i32 s36, s21, 0x100
	s_and_b64 s[30:31], s[28:29], exec
	s_cselect_b32 s31, 0, s36
	s_cselect_b32 s30, 0, 0
	s_add_u32 s36, s8, s31
	s_addc_u32 s37, s9, s30
	s_add_u32 s30, s24, s21
	s_addc_u32 s31, s25, 0
	s_add_u32 s30, s30, 0x100
	s_addc_u32 s31, s31, 0
	s_add_i32 s71, 0, 0x10000
	s_and_b64 s[28:29], s[28:29], exec
	s_cselect_b32 s39, s19, s31
	s_cselect_b32 s38, s18, s30
	s_add_i32 s29, 0, 0x14000
	s_add_u32 s21, s44, s21
	s_addc_u32 s28, s45, 0
	s_add_u32 s48, s21, 0x17110080
	s_addc_u32 s49, s28, 0
	s_add_i32 s70, s71, s52
	s_add_i32 m0, s53, 0xc000
	s_add_i32 s73, s53, 0xe000
	s_add_i32 s67, s70, 0x2000
	v_add_u32_e32 v134, s71, v136
	s_add_u32 s46, s38, 0x10000
	ds_read_b128 v[138:141], v134
	ds_read_b128 v[142:145], v134 offset:1024
	ds_read_b128 v[146:149], v134 offset:2048
	ds_read_b128 v[150:153], v134 offset:3072
	v_add_u32_e32 v134, s29, v136
	s_addc_u32 s47, s39, 0
	s_add_i32 s69, s29, s52
	ds_read_b128 v[154:157], v134
	ds_read_b128 v[158:161], v134 offset:1024
	ds_read_b128 v[162:165], v134 offset:2048
	ds_read_b128 v[166:169], v134 offset:3072
	s_add_i32 s68, s69, 0x2000
	s_add_i32 s66, 0, 0x18000
	s_add_i32 s65, 0, 0x1c000
	s_add_u32 s30, s36, 0x10000
	s_addc_u32 s31, s37, 0
	s_add_i32 s64, s66, s52
	s_add_i32 s21, s64, 0x2000
	s_add_u32 s28, s38, 0x10080
	s_addc_u32 s29, s39, 0
	s_add_i32 s72, s65, s52
	s_add_i32 s71, s72, 0x2000
	v_lshl_add_u64 v[134:135], s[48:49], 0, v[132:133]
	ds_read_b128 v[170:173], v137
	ds_read_b128 v[174:177], v137 offset:1024
	ds_read_b128 v[178:181], v137 offset:2048
	ds_read_b128 v[182:185], v137 offset:3072
	ds_read_b128 v[186:189], v137 offset:4096
	ds_read_b128 v[190:193], v137 offset:5120
	ds_read_b128 v[202:205], v137 offset:6144
	ds_read_b128 v[206:209], v137 offset:7168
	global_load_lds_dwordx4 v[134:135], off
	v_lshl_add_u64 v[134:135], s[48:49], 0, v[130:131]
	s_mov_b32 m0, s73
	s_nop 0
	global_load_lds_dwordx4 v[134:135], off
	s_waitcnt vmcnt(8)
	s_waitcnt lgkmcnt(0)
	s_setprio 1
	s_barrier
	v_mfma_f32_16x16x32_bf16 v[126:129], v[138:141], v[170:173], v[126:129]
	v_mfma_f32_16x16x32_bf16 v[126:129], v[142:145], v[174:177], v[126:129]
	v_mfma_f32_16x16x32_bf16 v[118:121], v[142:145], v[182:185], v[118:121]
	v_mfma_f32_16x16x32_bf16 v[118:121], v[138:141], v[178:181], v[118:121]
	v_mfma_f32_16x16x32_bf16 v[102:105], v[138:141], v[186:189], v[102:105]
	v_mfma_f32_16x16x32_bf16 v[102:105], v[142:145], v[190:193], v[102:105]
	v_mfma_f32_16x16x32_bf16 v[86:89], v[142:145], v[206:209], v[86:89]
	v_mfma_f32_16x16x32_bf16 v[86:89], v[138:141], v[202:205], v[86:89]
	v_mfma_f32_16x16x32_bf16 v[78:81], v[146:149], v[202:205], v[78:81]
	v_mfma_f32_16x16x32_bf16 v[78:81], v[150:153], v[206:209], v[78:81]
	v_mfma_f32_16x16x32_bf16 v[94:97], v[150:153], v[190:193], v[94:97]
	v_mfma_f32_16x16x32_bf16 v[94:97], v[146:149], v[186:189], v[94:97]
	v_mfma_f32_16x16x32_bf16 v[110:113], v[146:149], v[178:181], v[110:113]
	v_mfma_f32_16x16x32_bf16 v[110:113], v[150:153], v[182:185], v[110:113]
	v_mfma_f32_16x16x32_bf16 v[122:125], v[150:153], v[174:177], v[122:125]
	v_mfma_f32_16x16x32_bf16 v[122:125], v[146:149], v[170:173], v[122:125]
	v_mfma_f32_16x16x32_bf16 v[114:117], v[154:157], v[170:173], v[114:117]
	v_mfma_f32_16x16x32_bf16 v[114:117], v[158:161], v[174:177], v[114:117]
	v_mfma_f32_16x16x32_bf16 v[98:101], v[158:161], v[182:185], v[98:101]
	v_mfma_f32_16x16x32_bf16 v[98:101], v[154:157], v[178:181], v[98:101]
	v_mfma_f32_16x16x32_bf16 v[82:85], v[154:157], v[186:189], v[82:85]
	v_mfma_f32_16x16x32_bf16 v[82:85], v[158:161], v[190:193], v[82:85]
	v_mfma_f32_16x16x32_bf16 v[70:73], v[158:161], v[206:209], v[70:73]
	v_mfma_f32_16x16x32_bf16 v[70:73], v[154:157], v[202:205], v[70:73]
	v_mfma_f32_16x16x32_bf16 v[66:69], v[162:165], v[202:205], v[66:69]
	v_mfma_f32_16x16x32_bf16 v[66:69], v[166:169], v[206:209], v[66:69]
	v_mfma_f32_16x16x32_bf16 v[74:77], v[166:169], v[190:193], v[74:77]
	v_mfma_f32_16x16x32_bf16 v[74:77], v[162:165], v[186:189], v[74:77]
	v_mfma_f32_16x16x32_bf16 v[90:93], v[162:165], v[178:181], v[90:93]
	v_mfma_f32_16x16x32_bf16 v[90:93], v[166:169], v[182:185], v[90:93]
	v_mfma_f32_16x16x32_bf16 v[106:109], v[166:169], v[174:177], v[106:109]
	v_mfma_f32_16x16x32_bf16 v[106:109], v[162:165], v[170:173], v[106:109]
	s_barrier
	s_setprio 0
	s_mov_b32 m0, s70
	v_lshl_add_u64 v[134:135], s[38:39], 0, v[132:133]
	ds_read_b128 v[170:173], v137 offset:16384
	ds_read_b128 v[174:177], v137 offset:17408
	ds_read_b128 v[178:181], v137 offset:18432
	ds_read_b128 v[182:185], v137 offset:19456
	ds_read_b128 v[186:189], v137 offset:20480
	ds_read_b128 v[190:193], v137 offset:21504
	ds_read_b128 v[202:205], v137 offset:22528
	ds_read_b128 v[206:209], v137 offset:23552
	global_load_lds_dwordx4 v[134:135], off
	v_lshl_add_u64 v[210:211], s[38:39], 0, v[130:131]
	s_mov_b32 m0, s67
	v_lshl_add_u64 v[212:213], s[46:47], 0, v[132:133]
	global_load_lds_dwordx4 v[210:211], off
	s_mov_b32 m0, s69
	v_lshl_add_u64 v[214:215], s[36:37], 0, v[130:131]
	global_load_lds_dwordx4 v[212:213], off
	v_lshl_add_u64 v[212:213], s[46:47], 0, v[130:131]
	s_mov_b32 m0, s68
	s_nop 0
	global_load_lds_dwordx4 v[212:213], off
	v_lshl_add_u64 v[212:213], s[36:37], 0, v[132:133]
	s_mov_b32 m0, s53
	s_nop 0
	global_load_lds_dwordx4 v[212:213], off
	s_mov_b32 m0, s56
	s_nop 0
	global_load_lds_dwordx4 v[214:215], off
	s_waitcnt vmcnt(8)
	s_waitcnt lgkmcnt(0)
	s_setprio 1
	s_barrier
	v_mfma_f32_16x16x32_bf16 v[62:65], v[138:141], v[170:173], v[62:65]
	v_mfma_f32_16x16x32_bf16 v[62:65], v[142:145], v[174:177], v[62:65]
	v_mfma_f32_16x16x32_bf16 v[54:57], v[142:145], v[182:185], v[54:57]
	v_mfma_f32_16x16x32_bf16 v[54:57], v[138:141], v[178:181], v[54:57]
	v_mfma_f32_16x16x32_bf16 v[38:41], v[138:141], v[186:189], v[38:41]
	v_mfma_f32_16x16x32_bf16 v[38:41], v[142:145], v[190:193], v[38:41]
	v_mfma_f32_16x16x32_bf16 v[22:25], v[142:145], v[206:209], v[22:25]
	v_mfma_f32_16x16x32_bf16 v[22:25], v[138:141], v[202:205], v[22:25]
	v_mfma_f32_16x16x32_bf16 v[14:17], v[146:149], v[202:205], v[14:17]
	v_mfma_f32_16x16x32_bf16 v[14:17], v[150:153], v[206:209], v[14:17]
	v_mfma_f32_16x16x32_bf16 v[30:33], v[150:153], v[190:193], v[30:33]
	v_mfma_f32_16x16x32_bf16 v[30:33], v[146:149], v[186:189], v[30:33]
	v_mfma_f32_16x16x32_bf16 v[46:49], v[146:149], v[178:181], v[46:49]
	v_mfma_f32_16x16x32_bf16 v[46:49], v[150:153], v[182:185], v[46:49]
	v_mfma_f32_16x16x32_bf16 v[58:61], v[150:153], v[174:177], v[58:61]
	v_mfma_f32_16x16x32_bf16 v[58:61], v[146:149], v[170:173], v[58:61]
	v_mfma_f32_16x16x32_bf16 v[50:53], v[154:157], v[170:173], v[50:53]
	v_mfma_f32_16x16x32_bf16 v[50:53], v[158:161], v[174:177], v[50:53]
	v_mfma_f32_16x16x32_bf16 v[34:37], v[158:161], v[182:185], v[34:37]
	v_mfma_f32_16x16x32_bf16 v[34:37], v[154:157], v[178:181], v[34:37]
	v_mfma_f32_16x16x32_bf16 v[18:21], v[154:157], v[186:189], v[18:21]
	v_mfma_f32_16x16x32_bf16 v[18:21], v[158:161], v[190:193], v[18:21]
	v_mfma_f32_16x16x32_bf16 v[6:9], v[158:161], v[206:209], v[6:9]
	v_mfma_f32_16x16x32_bf16 v[6:9], v[154:157], v[202:205], v[6:9]
	v_mfma_f32_16x16x32_bf16 v[2:5], v[162:165], v[202:205], v[2:5]
	v_mfma_f32_16x16x32_bf16 v[2:5], v[166:169], v[206:209], v[2:5]
	v_mfma_f32_16x16x32_bf16 v[10:13], v[166:169], v[190:193], v[10:13]
	v_mfma_f32_16x16x32_bf16 v[10:13], v[162:165], v[186:189], v[10:13]
	v_mfma_f32_16x16x32_bf16 v[26:29], v[162:165], v[178:181], v[26:29]
	v_mfma_f32_16x16x32_bf16 v[26:29], v[166:169], v[182:185], v[26:29]
	v_mfma_f32_16x16x32_bf16 v[42:45], v[166:169], v[174:177], v[42:45]
	v_mfma_f32_16x16x32_bf16 v[42:45], v[162:165], v[170:173], v[42:45]
	s_barrier
	s_setprio 0
	v_add_u32_e32 v150, s66, v136
	v_add_u32_e32 v166, s65, v136
	ds_read_b128 v[138:141], v150
	ds_read_b128 v[142:145], v150 offset:1024
	ds_read_b128 v[146:149], v150 offset:2048
	ds_read_b128 v[150:153], v150 offset:3072
	ds_read_b128 v[154:157], v166
	ds_read_b128 v[158:161], v166 offset:1024
	ds_read_b128 v[162:165], v166 offset:2048
	ds_read_b128 v[166:169], v166 offset:3072
	s_mov_b32 m0, s57
	v_lshl_add_u64 v[216:217], s[30:31], 0, v[132:133]
	ds_read_b128 v[170:173], v137 offset:32768
	ds_read_b128 v[174:177], v137 offset:33792
	ds_read_b128 v[178:181], v137 offset:34816
	ds_read_b128 v[182:185], v137 offset:35840
	ds_read_b128 v[186:189], v137 offset:36864
	ds_read_b128 v[190:193], v137 offset:37888
	ds_read_b128 v[202:205], v137 offset:38912
	ds_read_b128 v[206:209], v137 offset:39936
	global_load_lds_dwordx4 v[216:217], off
	v_lshl_add_u64 v[216:217], s[30:31], 0, v[130:131]
	s_mov_b32 m0, s58
	s_nop 0
	global_load_lds_dwordx4 v[216:217], off
	s_waitcnt vmcnt(8)
	s_waitcnt lgkmcnt(0)
	s_setprio 1
	s_barrier
	v_mfma_f32_16x16x32_bf16 v[126:129], v[138:141], v[170:173], v[126:129]
	v_mfma_f32_16x16x32_bf16 v[126:129], v[142:145], v[174:177], v[126:129]
	v_mfma_f32_16x16x32_bf16 v[118:121], v[142:145], v[182:185], v[118:121]
	v_mfma_f32_16x16x32_bf16 v[118:121], v[138:141], v[178:181], v[118:121]
	v_mfma_f32_16x16x32_bf16 v[102:105], v[138:141], v[186:189], v[102:105]
	v_mfma_f32_16x16x32_bf16 v[102:105], v[142:145], v[190:193], v[102:105]
	v_mfma_f32_16x16x32_bf16 v[86:89], v[142:145], v[206:209], v[86:89]
	v_mfma_f32_16x16x32_bf16 v[86:89], v[138:141], v[202:205], v[86:89]
	v_mfma_f32_16x16x32_bf16 v[78:81], v[146:149], v[202:205], v[78:81]
	v_mfma_f32_16x16x32_bf16 v[78:81], v[150:153], v[206:209], v[78:81]
	v_mfma_f32_16x16x32_bf16 v[94:97], v[150:153], v[190:193], v[94:97]
	v_mfma_f32_16x16x32_bf16 v[94:97], v[146:149], v[186:189], v[94:97]
	v_mfma_f32_16x16x32_bf16 v[110:113], v[146:149], v[178:181], v[110:113]
	v_mfma_f32_16x16x32_bf16 v[110:113], v[150:153], v[182:185], v[110:113]
	v_mfma_f32_16x16x32_bf16 v[122:125], v[150:153], v[174:177], v[122:125]
	v_mfma_f32_16x16x32_bf16 v[122:125], v[146:149], v[170:173], v[122:125]
	v_mfma_f32_16x16x32_bf16 v[114:117], v[154:157], v[170:173], v[114:117]
	v_mfma_f32_16x16x32_bf16 v[114:117], v[158:161], v[174:177], v[114:117]
	v_mfma_f32_16x16x32_bf16 v[98:101], v[158:161], v[182:185], v[98:101]
	v_mfma_f32_16x16x32_bf16 v[98:101], v[154:157], v[178:181], v[98:101]
	v_mfma_f32_16x16x32_bf16 v[82:85], v[154:157], v[186:189], v[82:85]
	v_mfma_f32_16x16x32_bf16 v[82:85], v[158:161], v[190:193], v[82:85]
	v_mfma_f32_16x16x32_bf16 v[70:73], v[158:161], v[206:209], v[70:73]
	v_mfma_f32_16x16x32_bf16 v[70:73], v[154:157], v[202:205], v[70:73]
	v_mfma_f32_16x16x32_bf16 v[66:69], v[162:165], v[202:205], v[66:69]
	v_mfma_f32_16x16x32_bf16 v[66:69], v[166:169], v[206:209], v[66:69]
	v_mfma_f32_16x16x32_bf16 v[74:77], v[166:169], v[190:193], v[74:77]
	v_mfma_f32_16x16x32_bf16 v[74:77], v[162:165], v[186:189], v[74:77]
	v_mfma_f32_16x16x32_bf16 v[90:93], v[162:165], v[178:181], v[90:93]
	v_mfma_f32_16x16x32_bf16 v[90:93], v[166:169], v[182:185], v[90:93]
	v_mfma_f32_16x16x32_bf16 v[106:109], v[166:169], v[174:177], v[106:109]
	v_mfma_f32_16x16x32_bf16 v[106:109], v[162:165], v[170:173], v[106:109]
	s_barrier
	s_setprio 0
	s_mov_b32 m0, s64
	v_lshl_add_u64 v[134:135], v[134:135], 0, s[10:11]
	ds_read_b128 v[170:173], v137 offset:49152
	ds_read_b128 v[174:177], v137 offset:50176
	ds_read_b128 v[178:181], v137 offset:51200
	ds_read_b128 v[182:185], v137 offset:52224
	ds_read_b128 v[186:189], v137 offset:53248
	ds_read_b128 v[190:193], v137 offset:54272
	ds_read_b128 v[202:205], v137 offset:55296
	ds_read_b128 v[206:209], v137 offset:56320
	global_load_lds_dwordx4 v[134:135], off
	v_lshl_add_u64 v[134:135], v[210:211], 0, s[10:11]
	s_mov_b32 m0, s21
	s_nop 0
	global_load_lds_dwordx4 v[134:135], off
	v_lshl_add_u64 v[134:135], s[28:29], 0, v[132:133]
	s_mov_b32 m0, s72
	s_nop 0
	global_load_lds_dwordx4 v[134:135], off
	v_lshl_add_u64 v[134:135], s[28:29], 0, v[130:131]
	s_mov_b32 m0, s71
	s_nop 0
	global_load_lds_dwordx4 v[134:135], off
	v_lshl_add_u64 v[134:135], v[212:213], 0, s[10:11]
	s_mov_b32 m0, s59
	s_nop 0
	global_load_lds_dwordx4 v[134:135], off
	v_lshl_add_u64 v[134:135], v[214:215], 0, s[10:11]
	s_mov_b32 m0, s60
	s_nop 0
	global_load_lds_dwordx4 v[134:135], off
	s_waitcnt vmcnt(8)
	s_waitcnt lgkmcnt(0)
	s_setprio 1
	s_barrier
	v_mfma_f32_16x16x32_bf16 v[62:65], v[138:141], v[170:173], v[62:65]
	v_mfma_f32_16x16x32_bf16 v[62:65], v[142:145], v[174:177], v[62:65]
	v_mfma_f32_16x16x32_bf16 v[54:57], v[142:145], v[182:185], v[54:57]
	v_mfma_f32_16x16x32_bf16 v[54:57], v[138:141], v[178:181], v[54:57]
	v_mfma_f32_16x16x32_bf16 v[38:41], v[138:141], v[186:189], v[38:41]
	v_mfma_f32_16x16x32_bf16 v[38:41], v[142:145], v[190:193], v[38:41]
	v_mfma_f32_16x16x32_bf16 v[22:25], v[142:145], v[206:209], v[22:25]
	v_mfma_f32_16x16x32_bf16 v[22:25], v[138:141], v[202:205], v[22:25]
	v_mfma_f32_16x16x32_bf16 v[14:17], v[146:149], v[202:205], v[14:17]
	v_mfma_f32_16x16x32_bf16 v[14:17], v[150:153], v[206:209], v[14:17]
	v_mfma_f32_16x16x32_bf16 v[30:33], v[150:153], v[190:193], v[30:33]
	v_mfma_f32_16x16x32_bf16 v[30:33], v[146:149], v[186:189], v[30:33]
	v_mfma_f32_16x16x32_bf16 v[46:49], v[146:149], v[178:181], v[46:49]
	v_mfma_f32_16x16x32_bf16 v[46:49], v[150:153], v[182:185], v[46:49]
	v_mfma_f32_16x16x32_bf16 v[58:61], v[150:153], v[174:177], v[58:61]
	v_mfma_f32_16x16x32_bf16 v[58:61], v[146:149], v[170:173], v[58:61]
	v_mfma_f32_16x16x32_bf16 v[50:53], v[154:157], v[170:173], v[50:53]
	v_mfma_f32_16x16x32_bf16 v[50:53], v[158:161], v[174:177], v[50:53]
	v_mfma_f32_16x16x32_bf16 v[34:37], v[158:161], v[182:185], v[34:37]
	v_mfma_f32_16x16x32_bf16 v[34:37], v[154:157], v[178:181], v[34:37]
	v_mfma_f32_16x16x32_bf16 v[18:21], v[154:157], v[186:189], v[18:21]
	v_mfma_f32_16x16x32_bf16 v[18:21], v[158:161], v[190:193], v[18:21]
	v_mfma_f32_16x16x32_bf16 v[6:9], v[158:161], v[206:209], v[6:9]
	v_mfma_f32_16x16x32_bf16 v[6:9], v[154:157], v[202:205], v[6:9]
	v_mfma_f32_16x16x32_bf16 v[2:5], v[162:165], v[202:205], v[2:5]
	v_mfma_f32_16x16x32_bf16 v[2:5], v[166:169], v[206:209], v[2:5]
	v_mfma_f32_16x16x32_bf16 v[10:13], v[166:169], v[190:193], v[10:13]
	v_mfma_f32_16x16x32_bf16 v[10:13], v[162:165], v[186:189], v[10:13]
	v_mfma_f32_16x16x32_bf16 v[26:29], v[162:165], v[178:181], v[26:29]
	v_mfma_f32_16x16x32_bf16 v[26:29], v[166:169], v[182:185], v[26:29]
	v_mfma_f32_16x16x32_bf16 v[42:45], v[166:169], v[174:177], v[42:45]
	v_mfma_f32_16x16x32_bf16 v[42:45], v[162:165], v[170:173], v[42:45]
	s_barrier
	s_setprio 0
	s_andn2_b64 vcc, exec, s[26:27]
	s_mov_b64 s[28:29], -1
	s_mov_b64 s[26:27], 0
	s_movk_i32 s21, 0x100
	s_cbranch_vccz .LBB0_1002
	s_and_b64 vcc, exec, s[16:17]
	s_cbranch_vccz .LBB0_1005
	s_barrier

.LBB0_1087:
	s_add_u32 s30, s28, 0xfff80080
	s_addc_u32 s31, s29, -1
	s_cmp_eq_u32 s83, 28
	s_cselect_b32 s43, s23, s31
	s_cselect_b32 s42, s44, s30
	s_cselect_b32 s31, s21, s82
	s_cselect_b32 s30, s45, s81
	s_add_i32 s84, 0, 0x10000
	s_add_i32 s86, 0, 0x14000
	v_add_u32_e32 v62, s84, v229
	v_add_u32_e32 v158, s86, v229
	ds_read_b128 v[42:45], v62
	ds_read_b128 v[46:49], v62 offset:1024
	ds_read_b128 v[58:61], v62 offset:2048
	ds_read_b128 v[62:65], v62 offset:3072
	ds_read_b128 v[146:149], v158
	ds_read_b128 v[150:153], v158 offset:1024
	ds_read_b128 v[154:157], v158 offset:2048
	ds_read_b128 v[158:161], v158 offset:3072
	v_lshl_add_u64 v[208:209], s[28:29], 0, v[204:205]
	s_add_i32 m0, s71, 0xc000
	ds_read_b128 v[162:165], v230
	ds_read_b128 v[166:169], v230 offset:1024
	ds_read_b128 v[170:173], v230 offset:2048
	ds_read_b128 v[174:177], v230 offset:3072
	ds_read_b128 v[178:181], v230 offset:4096
	ds_read_b128 v[182:185], v230 offset:5120
	ds_read_b128 v[186:189], v230 offset:6144
	ds_read_b128 v[190:193], v230 offset:7168
	global_load_lds_dwordx4 v[208:209], off
	v_lshl_add_u64 v[208:209], s[28:29], 0, v[206:207]
	s_add_i32 m0, s71, 0xe000
	s_nop 0
	global_load_lds_dwordx4 v[208:209], off
	s_waitcnt vmcnt(8)
	s_waitcnt lgkmcnt(0)
	s_setprio 1
	s_barrier
	v_mfma_f32_16x16x32_bf16 v[142:145], v[42:45], v[162:165], v[142:145]
	v_mfma_f32_16x16x32_bf16 v[142:145], v[46:49], v[166:169], v[142:145]
	v_mfma_f32_16x16x32_bf16 v[126:129], v[46:49], v[174:177], v[126:129]
	v_mfma_f32_16x16x32_bf16 v[126:129], v[42:45], v[170:173], v[126:129]
	v_mfma_f32_16x16x32_bf16 v[110:113], v[42:45], v[178:181], v[110:113]
	v_mfma_f32_16x16x32_bf16 v[110:113], v[46:49], v[182:185], v[110:113]
	v_mfma_f32_16x16x32_bf16 v[94:97], v[46:49], v[190:193], v[94:97]
	v_mfma_f32_16x16x32_bf16 v[94:97], v[42:45], v[186:189], v[94:97]
	v_mfma_f32_16x16x32_bf16 v[90:93], v[58:61], v[186:189], v[90:93]
	v_mfma_f32_16x16x32_bf16 v[90:93], v[62:65], v[190:193], v[90:93]
	v_mfma_f32_16x16x32_bf16 v[106:109], v[62:65], v[182:185], v[106:109]
	v_mfma_f32_16x16x32_bf16 v[106:109], v[58:61], v[178:181], v[106:109]
	v_mfma_f32_16x16x32_bf16 v[122:125], v[58:61], v[170:173], v[122:125]
	v_mfma_f32_16x16x32_bf16 v[122:125], v[62:65], v[174:177], v[122:125]
	v_mfma_f32_16x16x32_bf16 v[138:141], v[62:65], v[166:169], v[138:141]
	v_mfma_f32_16x16x32_bf16 v[138:141], v[58:61], v[162:165], v[138:141]
	v_mfma_f32_16x16x32_bf16 v[134:137], v[146:149], v[162:165], v[134:137]
	v_mfma_f32_16x16x32_bf16 v[134:137], v[150:153], v[166:169], v[134:137]
	v_mfma_f32_16x16x32_bf16 v[118:121], v[150:153], v[174:177], v[118:121]
	v_mfma_f32_16x16x32_bf16 v[118:121], v[146:149], v[170:173], v[118:121]
	v_mfma_f32_16x16x32_bf16 v[102:105], v[146:149], v[178:181], v[102:105]
	v_mfma_f32_16x16x32_bf16 v[102:105], v[150:153], v[182:185], v[102:105]
	v_mfma_f32_16x16x32_bf16 v[86:89], v[150:153], v[190:193], v[86:89]
	v_mfma_f32_16x16x32_bf16 v[86:89], v[146:149], v[186:189], v[86:89]
	v_mfma_f32_16x16x32_bf16 v[82:85], v[154:157], v[186:189], v[82:85]
	v_mfma_f32_16x16x32_bf16 v[82:85], v[158:161], v[190:193], v[82:85]
	v_mfma_f32_16x16x32_bf16 v[98:101], v[158:161], v[182:185], v[98:101]
	v_mfma_f32_16x16x32_bf16 v[98:101], v[154:157], v[178:181], v[98:101]
	v_mfma_f32_16x16x32_bf16 v[114:117], v[154:157], v[170:173], v[114:117]
	v_mfma_f32_16x16x32_bf16 v[114:117], v[158:161], v[174:177], v[114:117]
	v_mfma_f32_16x16x32_bf16 v[130:133], v[158:161], v[166:169], v[130:133]
	v_mfma_f32_16x16x32_bf16 v[130:133], v[154:157], v[162:165], v[130:133]
	s_barrier
	s_setprio 0
	s_add_i32 s84, s84, s70
	v_lshl_add_u64 v[208:209], s[30:31], 0, v[194:195]
	s_mov_b32 m0, s84
	ds_read_b128 v[162:165], v230 offset:16384
	ds_read_b128 v[166:169], v230 offset:17408
	ds_read_b128 v[170:173], v230 offset:18432
	ds_read_b128 v[174:177], v230 offset:19456
	ds_read_b128 v[178:181], v230 offset:20480
	ds_read_b128 v[182:185], v230 offset:21504
	ds_read_b128 v[186:189], v230 offset:22528
	ds_read_b128 v[190:193], v230 offset:23552
	global_load_lds_dwordx4 v[208:209], off
	s_add_i32 m0, s84, 0x2000
	s_add_u32 s84, s30, 0x80000
	v_lshl_add_u64 v[210:211], s[30:31], 0, v[202:203]
	s_addc_u32 s85, s31, 0
	s_add_i32 s86, s86, s70
	global_load_lds_dwordx4 v[210:211], off
	v_lshl_add_u64 v[212:213], s[84:85], 0, v[194:195]
	s_mov_b32 m0, s86
	v_lshl_add_u64 v[214:215], s[42:43], 0, v[202:203]
	global_load_lds_dwordx4 v[212:213], off
	v_lshl_add_u64 v[212:213], s[84:85], 0, v[202:203]
	s_add_i32 m0, s86, 0x2000
	s_nop 0
	global_load_lds_dwordx4 v[212:213], off
	v_lshl_add_u64 v[212:213], s[42:43], 0, v[194:195]
	s_mov_b32 m0, s71
	s_nop 0
	global_load_lds_dwordx4 v[212:213], off
	s_mov_b32 m0, s72
	s_nop 0
	global_load_lds_dwordx4 v[214:215], off
	s_waitcnt vmcnt(8)
	s_waitcnt lgkmcnt(0)
	s_setprio 1
	s_barrier
	v_mfma_f32_16x16x32_bf16 v[78:81], v[42:45], v[162:165], v[78:81]
	v_mfma_f32_16x16x32_bf16 v[78:81], v[46:49], v[166:169], v[78:81]
	v_mfma_f32_16x16x32_bf16 v[54:57], v[46:49], v[174:177], v[54:57]
	v_mfma_f32_16x16x32_bf16 v[54:57], v[42:45], v[170:173], v[54:57]
	v_mfma_f32_16x16x32_bf16 v[30:33], v[42:45], v[178:181], v[30:33]
	v_mfma_f32_16x16x32_bf16 v[30:33], v[46:49], v[182:185], v[30:33]
	v_mfma_f32_16x16x32_bf16 v[14:17], v[46:49], v[190:193], v[14:17]
	v_mfma_f32_16x16x32_bf16 v[14:17], v[42:45], v[186:189], v[14:17]
	v_mfma_f32_16x16x32_bf16 v[10:13], v[58:61], v[186:189], v[10:13]
	v_mfma_f32_16x16x32_bf16 v[10:13], v[62:65], v[190:193], v[10:13]
	v_mfma_f32_16x16x32_bf16 v[26:29], v[62:65], v[182:185], v[26:29]
	v_mfma_f32_16x16x32_bf16 v[26:29], v[58:61], v[178:181], v[26:29]
	v_mfma_f32_16x16x32_bf16 v[50:53], v[58:61], v[170:173], v[50:53]
	v_mfma_f32_16x16x32_bf16 v[50:53], v[62:65], v[174:177], v[50:53]
	v_mfma_f32_16x16x32_bf16 v[74:77], v[62:65], v[166:169], v[74:77]
	v_mfma_f32_16x16x32_bf16 v[74:77], v[58:61], v[162:165], v[74:77]
	v_mfma_f32_16x16x32_bf16 v[38:41], v[146:149], v[170:173], v[38:41]
	v_mfma_f32_16x16x32_bf16 v[34:37], v[154:157], v[170:173], v[34:37]
	v_mfma_f32_16x16x32_bf16 v[22:25], v[146:149], v[178:181], v[22:25]
	v_mfma_f32_16x16x32_bf16 v[18:21], v[154:157], v[178:181], v[18:21]
	v_mfma_f32_16x16x32_bf16 v[6:9], v[146:149], v[186:189], v[6:9]
	v_mfma_f32_16x16x32_bf16 v[2:5], v[154:157], v[186:189], v[2:5]
	v_mfma_f32_16x16x32_bf16 v[42:45], v[146:149], v[162:165], v[70:73]
	v_mfma_f32_16x16x32_bf16 v[46:49], v[154:157], v[162:165], v[66:69]
	v_mfma_f32_16x16x32_bf16 v[38:41], v[150:153], v[174:177], v[38:41]
	v_mfma_f32_16x16x32_bf16 v[34:37], v[158:161], v[174:177], v[34:37]
	v_mfma_f32_16x16x32_bf16 v[22:25], v[150:153], v[182:185], v[22:25]
	v_mfma_f32_16x16x32_bf16 v[18:21], v[158:161], v[182:185], v[18:21]
	v_mfma_f32_16x16x32_bf16 v[6:9], v[150:153], v[190:193], v[6:9]
	v_mfma_f32_16x16x32_bf16 v[2:5], v[158:161], v[190:193], v[2:5]
	v_mfma_f32_16x16x32_bf16 v[42:45], v[150:153], v[166:169], v[42:45]
	v_mfma_f32_16x16x32_bf16 v[46:49], v[158:161], v[166:169], v[46:49]
	s_barrier
	s_setprio 0
	s_add_i32 s84, 0, 0x18000
	s_add_i32 s85, 0, 0x1c000
	v_add_u32_e32 v70, s84, v229
	v_add_u32_e32 v158, s85, v229
	ds_read_b128 v[58:61], v70
	ds_read_b128 v[62:65], v70 offset:1024
	ds_read_b128 v[66:69], v70 offset:2048
	ds_read_b128 v[70:73], v70 offset:3072
	ds_read_b128 v[146:149], v158
	ds_read_b128 v[150:153], v158 offset:1024
	ds_read_b128 v[154:157], v158 offset:2048
	ds_read_b128 v[158:161], v158 offset:3072
	s_add_u32 s42, s42, 0x80000
	s_addc_u32 s43, s43, 0
	s_mov_b32 m0, s73
	v_lshl_add_u64 v[216:217], s[42:43], 0, v[194:195]
	ds_read_b128 v[162:165], v230 offset:32768
	ds_read_b128 v[166:169], v230 offset:33792
	ds_read_b128 v[170:173], v230 offset:34816
	ds_read_b128 v[174:177], v230 offset:35840
	ds_read_b128 v[178:181], v230 offset:36864
	ds_read_b128 v[182:185], v230 offset:37888
	ds_read_b128 v[186:189], v230 offset:38912
	ds_read_b128 v[190:193], v230 offset:39936
	global_load_lds_dwordx4 v[216:217], off
	v_lshl_add_u64 v[216:217], s[42:43], 0, v[202:203]
	s_mov_b32 m0, s74
	s_nop 0
	global_load_lds_dwordx4 v[216:217], off
	s_waitcnt vmcnt(8)
	s_waitcnt lgkmcnt(0)
	s_setprio 1
	s_barrier
	v_mfma_f32_16x16x32_bf16 v[142:145], v[58:61], v[162:165], v[142:145]
	v_mfma_f32_16x16x32_bf16 v[142:145], v[62:65], v[166:169], v[142:145]
	v_mfma_f32_16x16x32_bf16 v[126:129], v[62:65], v[174:177], v[126:129]
	v_mfma_f32_16x16x32_bf16 v[126:129], v[58:61], v[170:173], v[126:129]
	v_mfma_f32_16x16x32_bf16 v[110:113], v[58:61], v[178:181], v[110:113]
	v_mfma_f32_16x16x32_bf16 v[110:113], v[62:65], v[182:185], v[110:113]
	v_mfma_f32_16x16x32_bf16 v[94:97], v[62:65], v[190:193], v[94:97]
	v_mfma_f32_16x16x32_bf16 v[94:97], v[58:61], v[186:189], v[94:97]
	v_mfma_f32_16x16x32_bf16 v[90:93], v[66:69], v[186:189], v[90:93]
	v_mfma_f32_16x16x32_bf16 v[90:93], v[70:73], v[190:193], v[90:93]
	v_mfma_f32_16x16x32_bf16 v[106:109], v[70:73], v[182:185], v[106:109]
	v_mfma_f32_16x16x32_bf16 v[106:109], v[66:69], v[178:181], v[106:109]
	v_mfma_f32_16x16x32_bf16 v[122:125], v[66:69], v[170:173], v[122:125]
	v_mfma_f32_16x16x32_bf16 v[122:125], v[70:73], v[174:177], v[122:125]
	v_mfma_f32_16x16x32_bf16 v[138:141], v[70:73], v[166:169], v[138:141]
	v_mfma_f32_16x16x32_bf16 v[138:141], v[66:69], v[162:165], v[138:141]
	v_mfma_f32_16x16x32_bf16 v[134:137], v[146:149], v[162:165], v[134:137]
	v_mfma_f32_16x16x32_bf16 v[134:137], v[150:153], v[166:169], v[134:137]
	v_mfma_f32_16x16x32_bf16 v[118:121], v[150:153], v[174:177], v[118:121]
	v_mfma_f32_16x16x32_bf16 v[118:121], v[146:149], v[170:173], v[118:121]
	v_mfma_f32_16x16x32_bf16 v[102:105], v[146:149], v[178:181], v[102:105]
	v_mfma_f32_16x16x32_bf16 v[102:105], v[150:153], v[182:185], v[102:105]
	v_mfma_f32_16x16x32_bf16 v[86:89], v[150:153], v[190:193], v[86:89]
	v_mfma_f32_16x16x32_bf16 v[86:89], v[146:149], v[186:189], v[86:89]
	v_mfma_f32_16x16x32_bf16 v[82:85], v[154:157], v[186:189], v[82:85]
	v_mfma_f32_16x16x32_bf16 v[82:85], v[158:161], v[190:193], v[82:85]
	v_mfma_f32_16x16x32_bf16 v[98:101], v[158:161], v[182:185], v[98:101]
	v_mfma_f32_16x16x32_bf16 v[98:101], v[154:157], v[178:181], v[98:101]
	v_mfma_f32_16x16x32_bf16 v[114:117], v[154:157], v[170:173], v[114:117]
	v_mfma_f32_16x16x32_bf16 v[114:117], v[158:161], v[174:177], v[114:117]
	v_mfma_f32_16x16x32_bf16 v[130:133], v[158:161], v[166:169], v[130:133]
	v_mfma_f32_16x16x32_bf16 v[130:133], v[154:157], v[162:165], v[130:133]
	s_barrier
	s_setprio 0
	s_add_i32 s42, s84, s70
	v_lshl_add_u64 v[208:209], v[208:209], 0, s[10:11]
	s_mov_b32 m0, s42
	ds_read_b128 v[162:165], v230 offset:49152
	ds_read_b128 v[166:169], v230 offset:50176
	ds_read_b128 v[170:173], v230 offset:51200
	ds_read_b128 v[174:177], v230 offset:52224
	ds_read_b128 v[178:181], v230 offset:53248
	ds_read_b128 v[182:185], v230 offset:54272
	ds_read_b128 v[186:189], v230 offset:55296
	ds_read_b128 v[190:193], v230 offset:56320
	global_load_lds_dwordx4 v[208:209], off
	s_add_i32 m0, s42, 0x2000
	s_add_u32 s30, s30, 0x80080
	v_lshl_add_u64 v[208:209], v[210:211], 0, s[10:11]
	s_addc_u32 s31, s31, 0
	s_add_i32 s42, s85, s70
	global_load_lds_dwordx4 v[208:209], off
	v_lshl_add_u64 v[208:209], s[30:31], 0, v[194:195]
	s_mov_b32 m0, s42
	s_nop 0
	global_load_lds_dwordx4 v[208:209], off
	v_lshl_add_u64 v[208:209], s[30:31], 0, v[202:203]
	s_add_i32 m0, s42, 0x2000
	s_nop 0
	global_load_lds_dwordx4 v[208:209], off
	v_lshl_add_u64 v[208:209], v[212:213], 0, s[10:11]
	s_mov_b32 m0, s79
	s_nop 0
	global_load_lds_dwordx4 v[208:209], off
	v_lshl_add_u64 v[208:209], v[214:215], 0, s[10:11]
	s_mov_b32 m0, s80
	s_nop 0
	global_load_lds_dwordx4 v[208:209], off
	s_waitcnt vmcnt(8)
	s_waitcnt lgkmcnt(0)
	s_setprio 1
	s_barrier
	v_mfma_f32_16x16x32_bf16 v[78:81], v[58:61], v[162:165], v[78:81]
	v_mfma_f32_16x16x32_bf16 v[78:81], v[62:65], v[166:169], v[78:81]
	v_mfma_f32_16x16x32_bf16 v[54:57], v[62:65], v[174:177], v[54:57]
	v_mfma_f32_16x16x32_bf16 v[54:57], v[58:61], v[170:173], v[54:57]
	v_mfma_f32_16x16x32_bf16 v[30:33], v[58:61], v[178:181], v[30:33]
	v_mfma_f32_16x16x32_bf16 v[30:33], v[62:65], v[182:185], v[30:33]
	v_mfma_f32_16x16x32_bf16 v[14:17], v[62:65], v[190:193], v[14:17]
	v_mfma_f32_16x16x32_bf16 v[14:17], v[58:61], v[186:189], v[14:17]
	v_mfma_f32_16x16x32_bf16 v[10:13], v[66:69], v[186:189], v[10:13]
	v_mfma_f32_16x16x32_bf16 v[10:13], v[70:73], v[190:193], v[10:13]
	v_mfma_f32_16x16x32_bf16 v[26:29], v[70:73], v[182:185], v[26:29]
	v_mfma_f32_16x16x32_bf16 v[26:29], v[66:69], v[178:181], v[26:29]
	v_mfma_f32_16x16x32_bf16 v[50:53], v[66:69], v[170:173], v[50:53]
	v_mfma_f32_16x16x32_bf16 v[50:53], v[70:73], v[174:177], v[50:53]
	v_mfma_f32_16x16x32_bf16 v[74:77], v[70:73], v[166:169], v[74:77]
	v_mfma_f32_16x16x32_bf16 v[74:77], v[66:69], v[162:165], v[74:77]
	v_mfma_f32_16x16x32_bf16 v[42:45], v[146:149], v[162:165], v[42:45]
	v_mfma_f32_16x16x32_bf16 v[70:73], v[150:153], v[166:169], v[42:45]
	v_mfma_f32_16x16x32_bf16 v[42:45], v[154:157], v[162:165], v[46:49]
	v_mfma_f32_16x16x32_bf16 v[38:41], v[146:149], v[170:173], v[38:41]
	v_mfma_f32_16x16x32_bf16 v[34:37], v[154:157], v[170:173], v[34:37]
	v_mfma_f32_16x16x32_bf16 v[22:25], v[146:149], v[178:181], v[22:25]
	v_mfma_f32_16x16x32_bf16 v[18:21], v[154:157], v[178:181], v[18:21]
	v_mfma_f32_16x16x32_bf16 v[6:9], v[146:149], v[186:189], v[6:9]
	v_mfma_f32_16x16x32_bf16 v[2:5], v[154:157], v[186:189], v[2:5]
	v_mfma_f32_16x16x32_bf16 v[66:69], v[158:161], v[166:169], v[42:45]
	v_mfma_f32_16x16x32_bf16 v[38:41], v[150:153], v[174:177], v[38:41]
	v_mfma_f32_16x16x32_bf16 v[34:37], v[158:161], v[174:177], v[34:37]
	v_mfma_f32_16x16x32_bf16 v[22:25], v[150:153], v[182:185], v[22:25]
	v_mfma_f32_16x16x32_bf16 v[18:21], v[158:161], v[182:185], v[18:21]
	v_mfma_f32_16x16x32_bf16 v[6:9], v[150:153], v[190:193], v[6:9]
	v_mfma_f32_16x16x32_bf16 v[2:5], v[158:161], v[190:193], v[2:5]
	s_barrier
	s_setprio 0
	s_add_i32 s83, s83, 2
	s_add_u32 s28, s28, 0x100
	s_addc_u32 s29, s29, 0
	s_add_u32 s81, s81, 0x100
	s_addc_u32 s82, s82, 0
	s_cmp_gt_u32 s83, 29
	s_cbranch_scc0 .LBB0_1087
	s_and_b64 vcc, exec, s[16:17]
	s_cbranch_vccz .LBB0_1090
	s_barrier

.LBB0_1272:
	s_add_u32 s30, s28, 0xfff80080
	s_addc_u32 s31, s29, -1
	s_add_i32 s66, 0, 0x10000
	s_cmp_eq_u32 s65, 28
	s_cselect_b32 s37, s60, s31
	s_cselect_b32 s36, s61, s30
	s_cselect_b32 s31, s21, s64
	s_cselect_b32 s30, s62, s63
	s_add_i32 s68, 0, 0x14000
	v_add_u32_e32 v126, s66, v156
	v_add_u32_e32 v154, s68, v156
	ds_read_b128 v[114:117], v126
	ds_read_b128 v[118:121], v126 offset:1024
	ds_read_b128 v[122:125], v126 offset:2048
	ds_read_b128 v[126:129], v126 offset:3072
	ds_read_b128 v[158:161], v154
	ds_read_b128 v[162:165], v154 offset:1024
	ds_read_b128 v[166:169], v154 offset:2048
	ds_read_b128 v[170:173], v154 offset:3072
	v_lshl_add_u64 v[154:155], s[28:29], 0, v[150:151]
	s_add_i32 m0, s49, 0xc000
	ds_read_b128 v[174:177], v157
	ds_read_b128 v[178:181], v157 offset:1024
	ds_read_b128 v[182:185], v157 offset:2048
	ds_read_b128 v[186:189], v157 offset:3072
	ds_read_b128 v[190:193], v157 offset:4096
	ds_read_b128 v[202:205], v157 offset:5120
	ds_read_b128 v[206:209], v157 offset:6144
	ds_read_b128 v[210:213], v157 offset:7168
	global_load_lds_dwordx4 v[154:155], off
	v_lshl_add_u64 v[154:155], s[28:29], 0, v[152:153]
	s_add_i32 m0, s49, 0xe000
	s_nop 0
	global_load_lds_dwordx4 v[154:155], off
	s_waitcnt vmcnt(8)
	s_waitcnt lgkmcnt(0)
	s_setprio 1
	s_barrier
	v_mfma_f32_16x16x32_bf16 v[142:145], v[114:117], v[174:177], v[142:145]
	v_mfma_f32_16x16x32_bf16 v[142:145], v[118:121], v[178:181], v[142:145]
	v_mfma_f32_16x16x32_bf16 v[110:113], v[118:121], v[186:189], v[110:113]
	v_mfma_f32_16x16x32_bf16 v[110:113], v[114:117], v[182:185], v[110:113]
	v_mfma_f32_16x16x32_bf16 v[94:97], v[114:117], v[190:193], v[94:97]
	v_mfma_f32_16x16x32_bf16 v[94:97], v[118:121], v[202:205], v[94:97]
	v_mfma_f32_16x16x32_bf16 v[78:81], v[118:121], v[210:213], v[78:81]
	v_mfma_f32_16x16x32_bf16 v[78:81], v[114:117], v[206:209], v[78:81]
	v_mfma_f32_16x16x32_bf16 v[74:77], v[122:125], v[206:209], v[74:77]
	v_mfma_f32_16x16x32_bf16 v[74:77], v[126:129], v[210:213], v[74:77]
	v_mfma_f32_16x16x32_bf16 v[90:93], v[126:129], v[202:205], v[90:93]
	v_mfma_f32_16x16x32_bf16 v[90:93], v[122:125], v[190:193], v[90:93]
	v_mfma_f32_16x16x32_bf16 v[106:109], v[122:125], v[182:185], v[106:109]
	v_mfma_f32_16x16x32_bf16 v[106:109], v[126:129], v[186:189], v[106:109]
	v_mfma_f32_16x16x32_bf16 v[138:141], v[126:129], v[178:181], v[138:141]
	v_mfma_f32_16x16x32_bf16 v[138:141], v[122:125], v[174:177], v[138:141]
	v_mfma_f32_16x16x32_bf16 v[134:137], v[158:161], v[174:177], v[134:137]
	v_mfma_f32_16x16x32_bf16 v[134:137], v[162:165], v[178:181], v[134:137]
	v_mfma_f32_16x16x32_bf16 v[102:105], v[162:165], v[186:189], v[102:105]
	v_mfma_f32_16x16x32_bf16 v[102:105], v[158:161], v[182:185], v[102:105]
	v_mfma_f32_16x16x32_bf16 v[86:89], v[158:161], v[190:193], v[86:89]
	v_mfma_f32_16x16x32_bf16 v[86:89], v[162:165], v[202:205], v[86:89]
	v_mfma_f32_16x16x32_bf16 v[70:73], v[162:165], v[210:213], v[70:73]
	v_mfma_f32_16x16x32_bf16 v[70:73], v[158:161], v[206:209], v[70:73]
	v_mfma_f32_16x16x32_bf16 v[66:69], v[166:169], v[206:209], v[66:69]
	v_mfma_f32_16x16x32_bf16 v[66:69], v[170:173], v[210:213], v[66:69]
	v_mfma_f32_16x16x32_bf16 v[82:85], v[170:173], v[202:205], v[82:85]
	v_mfma_f32_16x16x32_bf16 v[82:85], v[166:169], v[190:193], v[82:85]
	v_mfma_f32_16x16x32_bf16 v[98:101], v[166:169], v[182:185], v[98:101]
	v_mfma_f32_16x16x32_bf16 v[98:101], v[170:173], v[186:189], v[98:101]
	v_mfma_f32_16x16x32_bf16 v[130:133], v[170:173], v[178:181], v[130:133]
	v_mfma_f32_16x16x32_bf16 v[130:133], v[166:169], v[174:177], v[130:133]
	s_barrier
	s_setprio 0
	s_add_i32 s66, s66, s48
	v_lshl_add_u64 v[154:155], s[30:31], 0, v[146:147]
	s_mov_b32 m0, s66
	ds_read_b128 v[174:177], v157 offset:16384
	ds_read_b128 v[178:181], v157 offset:17408
	ds_read_b128 v[182:185], v157 offset:18432
	ds_read_b128 v[186:189], v157 offset:19456
	ds_read_b128 v[190:193], v157 offset:20480
	ds_read_b128 v[202:205], v157 offset:21504
	ds_read_b128 v[206:209], v157 offset:22528
	ds_read_b128 v[210:213], v157 offset:23552
	global_load_lds_dwordx4 v[154:155], off
	s_add_i32 m0, s66, 0x2000
	s_add_u32 s66, s30, 0x80000
	v_lshl_add_u64 v[214:215], s[30:31], 0, v[148:149]
	s_addc_u32 s67, s31, 0
	s_add_i32 s68, s68, s48
	global_load_lds_dwordx4 v[214:215], off
	v_lshl_add_u64 v[216:217], s[66:67], 0, v[146:147]
	s_mov_b32 m0, s68
	v_lshl_add_u64 v[228:229], s[36:37], 0, v[148:149]
	global_load_lds_dwordx4 v[216:217], off
	v_lshl_add_u64 v[216:217], s[66:67], 0, v[148:149]
	s_add_i32 m0, s68, 0x2000
	s_nop 0
	global_load_lds_dwordx4 v[216:217], off
	v_lshl_add_u64 v[216:217], s[36:37], 0, v[146:147]
	s_mov_b32 m0, s49
	s_nop 0
	global_load_lds_dwordx4 v[216:217], off
	s_mov_b32 m0, s50
	s_nop 0
	global_load_lds_dwordx4 v[228:229], off
	s_waitcnt vmcnt(8)
	s_waitcnt lgkmcnt(0)
	s_setprio 1
	s_barrier
	v_mfma_f32_16x16x32_bf16 v[62:65], v[114:117], v[174:177], v[62:65]
	v_mfma_f32_16x16x32_bf16 v[62:65], v[118:121], v[178:181], v[62:65]
	v_mfma_f32_16x16x32_bf16 v[46:49], v[118:121], v[186:189], v[46:49]
	v_mfma_f32_16x16x32_bf16 v[46:49], v[114:117], v[182:185], v[46:49]
	v_mfma_f32_16x16x32_bf16 v[30:33], v[114:117], v[190:193], v[30:33]
	v_mfma_f32_16x16x32_bf16 v[30:33], v[118:121], v[202:205], v[30:33]
	v_mfma_f32_16x16x32_bf16 v[14:17], v[118:121], v[210:213], v[14:17]
	v_mfma_f32_16x16x32_bf16 v[14:17], v[114:117], v[206:209], v[14:17]
	v_mfma_f32_16x16x32_bf16 v[10:13], v[122:125], v[206:209], v[10:13]
	v_mfma_f32_16x16x32_bf16 v[10:13], v[126:129], v[210:213], v[10:13]
	v_mfma_f32_16x16x32_bf16 v[26:29], v[126:129], v[202:205], v[26:29]
	v_mfma_f32_16x16x32_bf16 v[26:29], v[122:125], v[190:193], v[26:29]
	v_mfma_f32_16x16x32_bf16 v[42:45], v[122:125], v[182:185], v[42:45]
	v_mfma_f32_16x16x32_bf16 v[42:45], v[126:129], v[186:189], v[42:45]
	v_mfma_f32_16x16x32_bf16 v[58:61], v[126:129], v[178:181], v[58:61]
	v_mfma_f32_16x16x32_bf16 v[58:61], v[122:125], v[174:177], v[58:61]
	v_mfma_f32_16x16x32_bf16 v[54:57], v[158:161], v[174:177], v[54:57]
	v_mfma_f32_16x16x32_bf16 v[54:57], v[162:165], v[178:181], v[54:57]
	v_mfma_f32_16x16x32_bf16 v[38:41], v[162:165], v[186:189], v[38:41]
	v_mfma_f32_16x16x32_bf16 v[38:41], v[158:161], v[182:185], v[38:41]
	v_mfma_f32_16x16x32_bf16 v[22:25], v[158:161], v[190:193], v[22:25]
	v_mfma_f32_16x16x32_bf16 v[22:25], v[162:165], v[202:205], v[22:25]
	v_mfma_f32_16x16x32_bf16 v[6:9], v[162:165], v[210:213], v[6:9]
	v_mfma_f32_16x16x32_bf16 v[6:9], v[158:161], v[206:209], v[6:9]
	v_mfma_f32_16x16x32_bf16 v[2:5], v[166:169], v[206:209], v[2:5]
	v_mfma_f32_16x16x32_bf16 v[2:5], v[170:173], v[210:213], v[2:5]
	v_mfma_f32_16x16x32_bf16 v[18:21], v[170:173], v[202:205], v[18:21]
	v_mfma_f32_16x16x32_bf16 v[18:21], v[166:169], v[190:193], v[18:21]
	v_mfma_f32_16x16x32_bf16 v[34:37], v[166:169], v[182:185], v[34:37]
	v_mfma_f32_16x16x32_bf16 v[34:37], v[170:173], v[186:189], v[34:37]
	v_mfma_f32_16x16x32_bf16 v[50:53], v[170:173], v[178:181], v[50:53]
	v_mfma_f32_16x16x32_bf16 v[50:53], v[166:169], v[174:177], v[50:53]
	s_barrier
	s_setprio 0
	s_add_i32 s66, 0, 0x18000
	s_add_i32 s67, 0, 0x1c000
	v_add_u32_e32 v126, s66, v156
	v_add_u32_e32 v170, s67, v156
	ds_read_b128 v[114:117], v126
	ds_read_b128 v[118:121], v126 offset:1024
	ds_read_b128 v[122:125], v126 offset:2048
	ds_read_b128 v[126:129], v126 offset:3072
	ds_read_b128 v[158:161], v170
	ds_read_b128 v[162:165], v170 offset:1024
	ds_read_b128 v[166:169], v170 offset:2048
	ds_read_b128 v[170:173], v170 offset:3072
	s_add_u32 s36, s36, 0x80000
	s_addc_u32 s37, s37, 0
	s_mov_b32 m0, s51
	v_lshl_add_u64 v[230:231], s[36:37], 0, v[146:147]
	ds_read_b128 v[174:177], v157 offset:32768
	ds_read_b128 v[178:181], v157 offset:33792
	ds_read_b128 v[182:185], v157 offset:34816
	ds_read_b128 v[186:189], v157 offset:35840
	ds_read_b128 v[190:193], v157 offset:36864
	ds_read_b128 v[202:205], v157 offset:37888
	ds_read_b128 v[206:209], v157 offset:38912
	ds_read_b128 v[210:213], v157 offset:39936
	global_load_lds_dwordx4 v[230:231], off
	v_lshl_add_u64 v[230:231], s[36:37], 0, v[148:149]
	s_mov_b32 m0, s52
	s_nop 0
	global_load_lds_dwordx4 v[230:231], off
	s_waitcnt vmcnt(8)
	s_waitcnt lgkmcnt(0)
	s_setprio 1
	s_barrier
	v_mfma_f32_16x16x32_bf16 v[142:145], v[114:117], v[174:177], v[142:145]
	v_mfma_f32_16x16x32_bf16 v[142:145], v[118:121], v[178:181], v[142:145]
	v_mfma_f32_16x16x32_bf16 v[110:113], v[118:121], v[186:189], v[110:113]
	v_mfma_f32_16x16x32_bf16 v[110:113], v[114:117], v[182:185], v[110:113]
	v_mfma_f32_16x16x32_bf16 v[94:97], v[114:117], v[190:193], v[94:97]
	v_mfma_f32_16x16x32_bf16 v[94:97], v[118:121], v[202:205], v[94:97]
	v_mfma_f32_16x16x32_bf16 v[78:81], v[118:121], v[210:213], v[78:81]
	v_mfma_f32_16x16x32_bf16 v[78:81], v[114:117], v[206:209], v[78:81]
	v_mfma_f32_16x16x32_bf16 v[74:77], v[122:125], v[206:209], v[74:77]
	v_mfma_f32_16x16x32_bf16 v[74:77], v[126:129], v[210:213], v[74:77]
	v_mfma_f32_16x16x32_bf16 v[90:93], v[126:129], v[202:205], v[90:93]
	v_mfma_f32_16x16x32_bf16 v[90:93], v[122:125], v[190:193], v[90:93]
	v_mfma_f32_16x16x32_bf16 v[106:109], v[122:125], v[182:185], v[106:109]
	v_mfma_f32_16x16x32_bf16 v[106:109], v[126:129], v[186:189], v[106:109]
	v_mfma_f32_16x16x32_bf16 v[138:141], v[126:129], v[178:181], v[138:141]
	v_mfma_f32_16x16x32_bf16 v[138:141], v[122:125], v[174:177], v[138:141]
	v_mfma_f32_16x16x32_bf16 v[134:137], v[158:161], v[174:177], v[134:137]
	v_mfma_f32_16x16x32_bf16 v[134:137], v[162:165], v[178:181], v[134:137]
	v_mfma_f32_16x16x32_bf16 v[102:105], v[162:165], v[186:189], v[102:105]
	v_mfma_f32_16x16x32_bf16 v[102:105], v[158:161], v[182:185], v[102:105]
	v_mfma_f32_16x16x32_bf16 v[86:89], v[158:161], v[190:193], v[86:89]
	v_mfma_f32_16x16x32_bf16 v[86:89], v[162:165], v[202:205], v[86:89]
	v_mfma_f32_16x16x32_bf16 v[70:73], v[162:165], v[210:213], v[70:73]
	v_mfma_f32_16x16x32_bf16 v[70:73], v[158:161], v[206:209], v[70:73]
	v_mfma_f32_16x16x32_bf16 v[66:69], v[166:169], v[206:209], v[66:69]
	v_mfma_f32_16x16x32_bf16 v[66:69], v[170:173], v[210:213], v[66:69]
	v_mfma_f32_16x16x32_bf16 v[82:85], v[170:173], v[202:205], v[82:85]
	v_mfma_f32_16x16x32_bf16 v[82:85], v[166:169], v[190:193], v[82:85]
	v_mfma_f32_16x16x32_bf16 v[98:101], v[166:169], v[182:185], v[98:101]
	v_mfma_f32_16x16x32_bf16 v[98:101], v[170:173], v[186:189], v[98:101]
	v_mfma_f32_16x16x32_bf16 v[130:133], v[170:173], v[178:181], v[130:133]
	v_mfma_f32_16x16x32_bf16 v[130:133], v[166:169], v[174:177], v[130:133]
	s_barrier
	s_setprio 0
	s_add_i32 s36, s66, s48
	v_lshl_add_u64 v[154:155], v[154:155], 0, s[10:11]
	s_mov_b32 m0, s36
	ds_read_b128 v[174:177], v157 offset:49152
	ds_read_b128 v[178:181], v157 offset:50176
	ds_read_b128 v[182:185], v157 offset:51200
	ds_read_b128 v[186:189], v157 offset:52224
	ds_read_b128 v[190:193], v157 offset:53248
	ds_read_b128 v[202:205], v157 offset:54272
	ds_read_b128 v[206:209], v157 offset:55296
	ds_read_b128 v[210:213], v157 offset:56320
	global_load_lds_dwordx4 v[154:155], off
	s_add_i32 m0, s36, 0x2000
	s_add_u32 s30, s30, 0x80080
	v_lshl_add_u64 v[154:155], v[214:215], 0, s[10:11]
	s_addc_u32 s31, s31, 0
	s_add_i32 s36, s67, s48
	global_load_lds_dwordx4 v[154:155], off
	v_lshl_add_u64 v[154:155], s[30:31], 0, v[146:147]
	s_mov_b32 m0, s36
	s_nop 0
	global_load_lds_dwordx4 v[154:155], off
	v_lshl_add_u64 v[154:155], s[30:31], 0, v[148:149]
	s_add_i32 m0, s36, 0x2000
	s_nop 0
	global_load_lds_dwordx4 v[154:155], off
	v_lshl_add_u64 v[154:155], v[216:217], 0, s[10:11]
	s_mov_b32 m0, s53
	s_nop 0
	global_load_lds_dwordx4 v[154:155], off
	v_lshl_add_u64 v[154:155], v[228:229], 0, s[10:11]
	s_mov_b32 m0, s56
	s_nop 0
	global_load_lds_dwordx4 v[154:155], off
	s_waitcnt vmcnt(8)
	s_waitcnt lgkmcnt(0)
	s_setprio 1
	s_barrier
	v_mfma_f32_16x16x32_bf16 v[62:65], v[114:117], v[174:177], v[62:65]
	v_mfma_f32_16x16x32_bf16 v[62:65], v[118:121], v[178:181], v[62:65]
	v_mfma_f32_16x16x32_bf16 v[46:49], v[118:121], v[186:189], v[46:49]
	v_mfma_f32_16x16x32_bf16 v[46:49], v[114:117], v[182:185], v[46:49]
	v_mfma_f32_16x16x32_bf16 v[30:33], v[114:117], v[190:193], v[30:33]
	v_mfma_f32_16x16x32_bf16 v[30:33], v[118:121], v[202:205], v[30:33]
	v_mfma_f32_16x16x32_bf16 v[14:17], v[118:121], v[210:213], v[14:17]
	v_mfma_f32_16x16x32_bf16 v[14:17], v[114:117], v[206:209], v[14:17]
	v_mfma_f32_16x16x32_bf16 v[10:13], v[122:125], v[206:209], v[10:13]
	v_mfma_f32_16x16x32_bf16 v[10:13], v[126:129], v[210:213], v[10:13]
	v_mfma_f32_16x16x32_bf16 v[26:29], v[126:129], v[202:205], v[26:29]
	v_mfma_f32_16x16x32_bf16 v[26:29], v[122:125], v[190:193], v[26:29]
	v_mfma_f32_16x16x32_bf16 v[42:45], v[122:125], v[182:185], v[42:45]
	v_mfma_f32_16x16x32_bf16 v[42:45], v[126:129], v[186:189], v[42:45]
	v_mfma_f32_16x16x32_bf16 v[58:61], v[126:129], v[178:181], v[58:61]
	v_mfma_f32_16x16x32_bf16 v[58:61], v[122:125], v[174:177], v[58:61]
	v_mfma_f32_16x16x32_bf16 v[54:57], v[158:161], v[174:177], v[54:57]
	v_mfma_f32_16x16x32_bf16 v[54:57], v[162:165], v[178:181], v[54:57]
	v_mfma_f32_16x16x32_bf16 v[38:41], v[162:165], v[186:189], v[38:41]
	v_mfma_f32_16x16x32_bf16 v[38:41], v[158:161], v[182:185], v[38:41]
	v_mfma_f32_16x16x32_bf16 v[22:25], v[158:161], v[190:193], v[22:25]
	v_mfma_f32_16x16x32_bf16 v[22:25], v[162:165], v[202:205], v[22:25]
	v_mfma_f32_16x16x32_bf16 v[6:9], v[162:165], v[210:213], v[6:9]
	v_mfma_f32_16x16x32_bf16 v[6:9], v[158:161], v[206:209], v[6:9]
	v_mfma_f32_16x16x32_bf16 v[2:5], v[166:169], v[206:209], v[2:5]
	v_mfma_f32_16x16x32_bf16 v[2:5], v[170:173], v[210:213], v[2:5]
	v_mfma_f32_16x16x32_bf16 v[18:21], v[170:173], v[202:205], v[18:21]
	v_mfma_f32_16x16x32_bf16 v[18:21], v[166:169], v[190:193], v[18:21]
	v_mfma_f32_16x16x32_bf16 v[34:37], v[166:169], v[182:185], v[34:37]
	v_mfma_f32_16x16x32_bf16 v[34:37], v[170:173], v[186:189], v[34:37]
	v_mfma_f32_16x16x32_bf16 v[50:53], v[170:173], v[178:181], v[50:53]
	v_mfma_f32_16x16x32_bf16 v[50:53], v[166:169], v[174:177], v[50:53]
	s_barrier
	s_setprio 0
	s_add_i32 s65, s65, 2
	s_add_u32 s28, s28, 0x100
	s_addc_u32 s29, s29, 0
	s_add_u32 s63, s63, 0x100
	s_addc_u32 s64, s64, 0
	s_cmp_gt_u32 s65, 29
	s_cbranch_scc0 .LBB0_1272
	s_and_b64 vcc, exec, s[18:19]
	s_cbranch_vccz .LBB0_1275
	s_barrier

.LBB0_1346:
	s_or_b32 s20, s30, 1
	s_mul_hi_u32 s31, s20, 0x280000
	s_mul_i32 s42, s20, 0x280000
	s_add_u32 s20, s56, s18
	s_addc_u32 s21, s57, s19
	s_add_u32 s18, s16, 0x280000
	s_addc_u32 s19, s17, 0
	s_add_i32 s44, 0, 0x10000
	s_add_i32 s45, 0, 0x14000
	v_add_u32_e32 v146, s44, v44
	v_add_u32_e32 v162, s45, v44
	ds_read_b128 v[46:49], v146
	ds_read_b128 v[58:61], v146 offset:1024
	ds_read_b128 v[62:65], v146 offset:2048
	ds_read_b128 v[146:149], v146 offset:3072
	ds_read_b128 v[150:153], v162
	ds_read_b128 v[154:157], v162 offset:1024
	ds_read_b128 v[158:161], v162 offset:2048
	ds_read_b128 v[162:165], v162 offset:3072
	s_add_u32 s42, s62, s42
	s_addc_u32 s43, s63, s31
	v_lshl_add_u64 v[206:207], s[42:43], 0, v[194:195]
	s_add_i32 m0, s24, 0xc000
	ds_read_b128 v[166:169], v45
	ds_read_b128 v[170:173], v45 offset:1024
	ds_read_b128 v[174:177], v45 offset:2048
	ds_read_b128 v[178:181], v45 offset:3072
	ds_read_b128 v[182:185], v45 offset:4096
	ds_read_b128 v[186:189], v45 offset:5120
	ds_read_b128 v[190:193], v45 offset:6144
	ds_read_b128 v[202:205], v45 offset:7168
	global_load_lds_dwordx4 v[206:207], off
	v_lshl_add_u64 v[206:207], s[42:43], 0, v[42:43]
	s_add_i32 m0, s24, 0xe000
	s_nop 0
	global_load_lds_dwordx4 v[206:207], off
	s_waitcnt vmcnt(8)
	s_waitcnt lgkmcnt(0)
	s_setprio 1
	s_barrier
	v_mfma_f32_16x16x32_bf16 v[142:145], v[46:49], v[166:169], v[142:145]
	v_mfma_f32_16x16x32_bf16 v[142:145], v[58:61], v[170:173], v[142:145]
	v_mfma_f32_16x16x32_bf16 v[126:129], v[58:61], v[178:181], v[126:129]
	v_mfma_f32_16x16x32_bf16 v[126:129], v[46:49], v[174:177], v[126:129]
	v_mfma_f32_16x16x32_bf16 v[110:113], v[46:49], v[182:185], v[110:113]
	v_mfma_f32_16x16x32_bf16 v[110:113], v[58:61], v[186:189], v[110:113]
	v_mfma_f32_16x16x32_bf16 v[94:97], v[58:61], v[202:205], v[94:97]
	v_mfma_f32_16x16x32_bf16 v[94:97], v[46:49], v[190:193], v[94:97]
	v_mfma_f32_16x16x32_bf16 v[90:93], v[62:65], v[190:193], v[90:93]
	v_mfma_f32_16x16x32_bf16 v[90:93], v[146:149], v[202:205], v[90:93]
	v_mfma_f32_16x16x32_bf16 v[106:109], v[146:149], v[186:189], v[106:109]
	v_mfma_f32_16x16x32_bf16 v[106:109], v[62:65], v[182:185], v[106:109]
	v_mfma_f32_16x16x32_bf16 v[122:125], v[62:65], v[174:177], v[122:125]
	v_mfma_f32_16x16x32_bf16 v[122:125], v[146:149], v[178:181], v[122:125]
	v_mfma_f32_16x16x32_bf16 v[138:141], v[146:149], v[170:173], v[138:141]
	v_mfma_f32_16x16x32_bf16 v[138:141], v[62:65], v[166:169], v[138:141]
	v_mfma_f32_16x16x32_bf16 v[134:137], v[150:153], v[166:169], v[134:137]
	v_mfma_f32_16x16x32_bf16 v[134:137], v[154:157], v[170:173], v[134:137]
	v_mfma_f32_16x16x32_bf16 v[118:121], v[154:157], v[178:181], v[118:121]
	v_mfma_f32_16x16x32_bf16 v[118:121], v[150:153], v[174:177], v[118:121]
	v_mfma_f32_16x16x32_bf16 v[102:105], v[150:153], v[182:185], v[102:105]
	v_mfma_f32_16x16x32_bf16 v[102:105], v[154:157], v[186:189], v[102:105]
	v_mfma_f32_16x16x32_bf16 v[86:89], v[154:157], v[202:205], v[86:89]
	v_mfma_f32_16x16x32_bf16 v[86:89], v[150:153], v[190:193], v[86:89]
	v_mfma_f32_16x16x32_bf16 v[82:85], v[158:161], v[190:193], v[82:85]
	v_mfma_f32_16x16x32_bf16 v[82:85], v[162:165], v[202:205], v[82:85]
	v_mfma_f32_16x16x32_bf16 v[98:101], v[162:165], v[186:189], v[98:101]
	v_mfma_f32_16x16x32_bf16 v[98:101], v[158:161], v[182:185], v[98:101]
	v_mfma_f32_16x16x32_bf16 v[114:117], v[158:161], v[174:177], v[114:117]
	v_mfma_f32_16x16x32_bf16 v[114:117], v[162:165], v[178:181], v[114:117]
	v_mfma_f32_16x16x32_bf16 v[130:133], v[162:165], v[170:173], v[130:133]
	v_mfma_f32_16x16x32_bf16 v[130:133], v[158:161], v[166:169], v[130:133]
	s_barrier
	s_setprio 0
	s_add_i32 s31, s44, s23
	v_lshl_add_u64 v[206:207], s[20:21], 0, v[194:195]
	s_mov_b32 m0, s31
	ds_read_b128 v[166:169], v45 offset:16384
	ds_read_b128 v[170:173], v45 offset:17408
	ds_read_b128 v[174:177], v45 offset:18432
	ds_read_b128 v[178:181], v45 offset:19456
	ds_read_b128 v[182:185], v45 offset:20480
	ds_read_b128 v[186:189], v45 offset:21504
	ds_read_b128 v[190:193], v45 offset:22528
	ds_read_b128 v[202:205], v45 offset:23552
	global_load_lds_dwordx4 v[206:207], off
	s_add_i32 m0, s31, 0x2000
	s_add_u32 s42, s20, 0x4000
	v_lshl_add_u64 v[206:207], s[20:21], 0, v[42:43]
	s_addc_u32 s43, s21, 0
	s_add_i32 s31, s45, s23
	global_load_lds_dwordx4 v[206:207], off
	v_lshl_add_u64 v[206:207], s[42:43], 0, v[194:195]
	s_mov_b32 m0, s31
	s_nop 0
	global_load_lds_dwordx4 v[206:207], off
	v_lshl_add_u64 v[206:207], s[42:43], 0, v[42:43]
	s_add_i32 m0, s31, 0x2000
	s_nop 0
	global_load_lds_dwordx4 v[206:207], off
	v_lshl_add_u64 v[206:207], s[16:17], 0, v[194:195]
	s_mov_b32 m0, s24
	s_nop 0
	global_load_lds_dwordx4 v[206:207], off
	v_lshl_add_u64 v[206:207], s[16:17], 0, v[42:43]
	s_mov_b32 m0, s25
	s_nop 0
	global_load_lds_dwordx4 v[206:207], off
	s_waitcnt vmcnt(8)
	s_waitcnt lgkmcnt(0)
	s_setprio 1
	s_barrier
	v_mfma_f32_16x16x32_bf16 v[78:81], v[46:49], v[166:169], v[78:81]
	v_mfma_f32_16x16x32_bf16 v[78:81], v[58:61], v[170:173], v[78:81]
	v_mfma_f32_16x16x32_bf16 v[54:57], v[58:61], v[178:181], v[54:57]
	v_mfma_f32_16x16x32_bf16 v[54:57], v[46:49], v[174:177], v[54:57]
	v_mfma_f32_16x16x32_bf16 v[30:33], v[46:49], v[182:185], v[30:33]
	v_mfma_f32_16x16x32_bf16 v[30:33], v[58:61], v[186:189], v[30:33]
	v_mfma_f32_16x16x32_bf16 v[14:17], v[58:61], v[202:205], v[14:17]
	v_mfma_f32_16x16x32_bf16 v[14:17], v[46:49], v[190:193], v[14:17]
	v_mfma_f32_16x16x32_bf16 v[10:13], v[62:65], v[190:193], v[10:13]
	v_mfma_f32_16x16x32_bf16 v[10:13], v[146:149], v[202:205], v[10:13]
	v_mfma_f32_16x16x32_bf16 v[26:29], v[146:149], v[186:189], v[26:29]
	v_mfma_f32_16x16x32_bf16 v[26:29], v[62:65], v[182:185], v[26:29]
	v_mfma_f32_16x16x32_bf16 v[50:53], v[62:65], v[174:177], v[50:53]
	v_mfma_f32_16x16x32_bf16 v[50:53], v[146:149], v[178:181], v[50:53]
	v_mfma_f32_16x16x32_bf16 v[74:77], v[146:149], v[170:173], v[74:77]
	v_mfma_f32_16x16x32_bf16 v[74:77], v[62:65], v[166:169], v[74:77]
	v_mfma_f32_16x16x32_bf16 v[38:41], v[150:153], v[174:177], v[38:41]
	v_mfma_f32_16x16x32_bf16 v[34:37], v[158:161], v[174:177], v[34:37]
	v_mfma_f32_16x16x32_bf16 v[22:25], v[150:153], v[182:185], v[22:25]
	v_mfma_f32_16x16x32_bf16 v[18:21], v[158:161], v[182:185], v[18:21]
	v_mfma_f32_16x16x32_bf16 v[6:9], v[150:153], v[190:193], v[6:9]
	v_mfma_f32_16x16x32_bf16 v[2:5], v[158:161], v[190:193], v[2:5]
	v_mfma_f32_16x16x32_bf16 v[46:49], v[150:153], v[166:169], v[70:73]
	v_mfma_f32_16x16x32_bf16 v[58:61], v[158:161], v[166:169], v[66:69]
	v_mfma_f32_16x16x32_bf16 v[38:41], v[154:157], v[178:181], v[38:41]
	v_mfma_f32_16x16x32_bf16 v[34:37], v[162:165], v[178:181], v[34:37]
	v_mfma_f32_16x16x32_bf16 v[22:25], v[154:157], v[186:189], v[22:25]
	v_mfma_f32_16x16x32_bf16 v[18:21], v[162:165], v[186:189], v[18:21]
	v_mfma_f32_16x16x32_bf16 v[6:9], v[154:157], v[202:205], v[6:9]
	v_mfma_f32_16x16x32_bf16 v[2:5], v[162:165], v[202:205], v[2:5]
	v_mfma_f32_16x16x32_bf16 v[46:49], v[154:157], v[170:173], v[46:49]
	v_mfma_f32_16x16x32_bf16 v[58:61], v[162:165], v[170:173], v[58:61]
	s_barrier
	s_setprio 0
	s_add_i32 s31, 0, 0x18000
	s_add_i32 s42, 0, 0x1c000
	v_add_u32_e32 v146, s31, v44
	v_add_u32_e32 v162, s42, v44
	ds_read_b128 v[62:65], v146
	ds_read_b128 v[66:69], v146 offset:1024
	ds_read_b128 v[70:73], v146 offset:2048
	ds_read_b128 v[146:149], v146 offset:3072
	ds_read_b128 v[150:153], v162
	ds_read_b128 v[154:157], v162 offset:1024
	ds_read_b128 v[158:161], v162 offset:2048
	ds_read_b128 v[162:165], v162 offset:3072
	s_add_u32 s16, s16, 0x4000
	s_addc_u32 s17, s17, 0
	s_mov_b32 m0, s26
	v_lshl_add_u64 v[206:207], s[16:17], 0, v[194:195]
	ds_read_b128 v[166:169], v45 offset:32768
	ds_read_b128 v[170:173], v45 offset:33792
	ds_read_b128 v[174:177], v45 offset:34816
	ds_read_b128 v[178:181], v45 offset:35840
	ds_read_b128 v[182:185], v45 offset:36864
	ds_read_b128 v[186:189], v45 offset:37888
	ds_read_b128 v[190:193], v45 offset:38912
	ds_read_b128 v[202:205], v45 offset:39936
	global_load_lds_dwordx4 v[206:207], off
	v_lshl_add_u64 v[206:207], s[16:17], 0, v[42:43]
	s_mov_b32 m0, s27
	s_nop 0
	global_load_lds_dwordx4 v[206:207], off
	s_waitcnt vmcnt(8)
	s_waitcnt lgkmcnt(0)
	s_setprio 1
	s_barrier
	v_mfma_f32_16x16x32_bf16 v[142:145], v[62:65], v[166:169], v[142:145]
	v_mfma_f32_16x16x32_bf16 v[142:145], v[66:69], v[170:173], v[142:145]
	v_mfma_f32_16x16x32_bf16 v[126:129], v[66:69], v[178:181], v[126:129]
	v_mfma_f32_16x16x32_bf16 v[126:129], v[62:65], v[174:177], v[126:129]
	v_mfma_f32_16x16x32_bf16 v[110:113], v[62:65], v[182:185], v[110:113]
	v_mfma_f32_16x16x32_bf16 v[110:113], v[66:69], v[186:189], v[110:113]
	v_mfma_f32_16x16x32_bf16 v[94:97], v[66:69], v[202:205], v[94:97]
	v_mfma_f32_16x16x32_bf16 v[94:97], v[62:65], v[190:193], v[94:97]
	v_mfma_f32_16x16x32_bf16 v[90:93], v[70:73], v[190:193], v[90:93]
	v_mfma_f32_16x16x32_bf16 v[90:93], v[146:149], v[202:205], v[90:93]
	v_mfma_f32_16x16x32_bf16 v[106:109], v[146:149], v[186:189], v[106:109]
	v_mfma_f32_16x16x32_bf16 v[106:109], v[70:73], v[182:185], v[106:109]
	v_mfma_f32_16x16x32_bf16 v[122:125], v[70:73], v[174:177], v[122:125]
	v_mfma_f32_16x16x32_bf16 v[122:125], v[146:149], v[178:181], v[122:125]
	v_mfma_f32_16x16x32_bf16 v[138:141], v[146:149], v[170:173], v[138:141]
	v_mfma_f32_16x16x32_bf16 v[138:141], v[70:73], v[166:169], v[138:141]
	v_mfma_f32_16x16x32_bf16 v[134:137], v[150:153], v[166:169], v[134:137]
	v_mfma_f32_16x16x32_bf16 v[134:137], v[154:157], v[170:173], v[134:137]
	v_mfma_f32_16x16x32_bf16 v[118:121], v[154:157], v[178:181], v[118:121]
	v_mfma_f32_16x16x32_bf16 v[118:121], v[150:153], v[174:177], v[118:121]
	v_mfma_f32_16x16x32_bf16 v[102:105], v[150:153], v[182:185], v[102:105]
	v_mfma_f32_16x16x32_bf16 v[102:105], v[154:157], v[186:189], v[102:105]
	v_mfma_f32_16x16x32_bf16 v[86:89], v[154:157], v[202:205], v[86:89]
	v_mfma_f32_16x16x32_bf16 v[86:89], v[150:153], v[190:193], v[86:89]
	v_mfma_f32_16x16x32_bf16 v[82:85], v[158:161], v[190:193], v[82:85]
	v_mfma_f32_16x16x32_bf16 v[82:85], v[162:165], v[202:205], v[82:85]
	v_mfma_f32_16x16x32_bf16 v[98:101], v[162:165], v[186:189], v[98:101]
	v_mfma_f32_16x16x32_bf16 v[98:101], v[158:161], v[182:185], v[98:101]
	v_mfma_f32_16x16x32_bf16 v[114:117], v[158:161], v[174:177], v[114:117]
	v_mfma_f32_16x16x32_bf16 v[114:117], v[162:165], v[178:181], v[114:117]
	v_mfma_f32_16x16x32_bf16 v[130:133], v[162:165], v[170:173], v[130:133]
	v_mfma_f32_16x16x32_bf16 v[130:133], v[158:161], v[166:169], v[130:133]
	s_barrier
	s_setprio 0
	s_add_u32 s16, s20, 0x40000
	s_addc_u32 s17, s21, 0
	s_add_i32 s31, s31, s23
	v_lshl_add_u64 v[206:207], s[16:17], 0, v[194:195]
	s_mov_b32 m0, s31
	ds_read_b128 v[166:169], v45 offset:49152
	ds_read_b128 v[170:173], v45 offset:50176
	ds_read_b128 v[174:177], v45 offset:51200
	ds_read_b128 v[178:181], v45 offset:52224
	ds_read_b128 v[182:185], v45 offset:53248
	ds_read_b128 v[186:189], v45 offset:54272
	ds_read_b128 v[190:193], v45 offset:55296
	ds_read_b128 v[202:205], v45 offset:56320
	global_load_lds_dwordx4 v[206:207], off
	s_add_i32 m0, s31, 0x2000
	v_lshl_add_u64 v[206:207], s[16:17], 0, v[42:43]
	s_add_u32 s16, s20, 0x44000
	s_addc_u32 s17, s21, 0
	s_add_i32 s20, s42, s23
	global_load_lds_dwordx4 v[206:207], off
	v_lshl_add_u64 v[206:207], s[16:17], 0, v[194:195]
	s_mov_b32 m0, s20
	s_nop 0
	global_load_lds_dwordx4 v[206:207], off
	v_lshl_add_u64 v[206:207], s[16:17], 0, v[42:43]
	s_add_i32 m0, s20, 0x2000
	s_nop 0
	global_load_lds_dwordx4 v[206:207], off
	v_lshl_add_u64 v[206:207], s[18:19], 0, v[194:195]
	s_mov_b32 m0, s28
	s_nop 0
	global_load_lds_dwordx4 v[206:207], off
	v_lshl_add_u64 v[206:207], s[18:19], 0, v[42:43]
	s_mov_b32 m0, s29
	s_nop 0
	global_load_lds_dwordx4 v[206:207], off
	s_waitcnt vmcnt(8)
	s_waitcnt lgkmcnt(0)
	s_setprio 1
	s_barrier
	v_mfma_f32_16x16x32_bf16 v[78:81], v[62:65], v[166:169], v[78:81]
	v_mfma_f32_16x16x32_bf16 v[78:81], v[66:69], v[170:173], v[78:81]
	v_mfma_f32_16x16x32_bf16 v[54:57], v[66:69], v[178:181], v[54:57]
	v_mfma_f32_16x16x32_bf16 v[54:57], v[62:65], v[174:177], v[54:57]
	v_mfma_f32_16x16x32_bf16 v[30:33], v[62:65], v[182:185], v[30:33]
	v_mfma_f32_16x16x32_bf16 v[30:33], v[66:69], v[186:189], v[30:33]
	v_mfma_f32_16x16x32_bf16 v[14:17], v[66:69], v[202:205], v[14:17]
	v_mfma_f32_16x16x32_bf16 v[14:17], v[62:65], v[190:193], v[14:17]
	v_mfma_f32_16x16x32_bf16 v[10:13], v[70:73], v[190:193], v[10:13]
	v_mfma_f32_16x16x32_bf16 v[10:13], v[146:149], v[202:205], v[10:13]
	v_mfma_f32_16x16x32_bf16 v[26:29], v[146:149], v[186:189], v[26:29]
	v_mfma_f32_16x16x32_bf16 v[26:29], v[70:73], v[182:185], v[26:29]
	v_mfma_f32_16x16x32_bf16 v[50:53], v[70:73], v[174:177], v[50:53]
	v_mfma_f32_16x16x32_bf16 v[50:53], v[146:149], v[178:181], v[50:53]
	v_mfma_f32_16x16x32_bf16 v[74:77], v[146:149], v[170:173], v[74:77]
	v_mfma_f32_16x16x32_bf16 v[74:77], v[70:73], v[166:169], v[74:77]
	v_mfma_f32_16x16x32_bf16 v[46:49], v[150:153], v[166:169], v[46:49]
	v_mfma_f32_16x16x32_bf16 v[70:73], v[154:157], v[170:173], v[46:49]
	v_mfma_f32_16x16x32_bf16 v[46:49], v[158:161], v[166:169], v[58:61]
	v_mfma_f32_16x16x32_bf16 v[38:41], v[150:153], v[174:177], v[38:41]
	v_mfma_f32_16x16x32_bf16 v[34:37], v[158:161], v[174:177], v[34:37]
	v_mfma_f32_16x16x32_bf16 v[22:25], v[150:153], v[182:185], v[22:25]
	v_mfma_f32_16x16x32_bf16 v[18:21], v[158:161], v[182:185], v[18:21]
	v_mfma_f32_16x16x32_bf16 v[6:9], v[150:153], v[190:193], v[6:9]
	v_mfma_f32_16x16x32_bf16 v[2:5], v[158:161], v[190:193], v[2:5]
	v_mfma_f32_16x16x32_bf16 v[66:69], v[162:165], v[170:173], v[46:49]
	v_mfma_f32_16x16x32_bf16 v[38:41], v[154:157], v[178:181], v[38:41]
	v_mfma_f32_16x16x32_bf16 v[34:37], v[162:165], v[178:181], v[34:37]
	v_mfma_f32_16x16x32_bf16 v[22:25], v[154:157], v[186:189], v[22:25]
	v_mfma_f32_16x16x32_bf16 v[18:21], v[162:165], v[186:189], v[18:21]
	v_mfma_f32_16x16x32_bf16 v[6:9], v[154:157], v[202:205], v[6:9]
	v_mfma_f32_16x16x32_bf16 v[2:5], v[162:165], v[202:205], v[2:5]
	s_barrier
	s_setprio 0
	s_cmp_gt_u32 s30, 61
	s_mov_b32 s30, s4
	s_cbranch_scc1 .LBB0_1349

.LBB0_1502:
	s_or_b32 s82, s81, 1
	s_add_u32 vcc_lo, s26, vcc_lo
	s_addc_u32 vcc_hi, s27, vcc_hi
	s_and_b64 s[46:47], exec, s[46:47]
	s_cselect_b32 vcc_hi, s19, vcc_hi
	s_cselect_b32 vcc_lo, s21, vcc_lo
	s_add_u32 s46, s44, 0x280000
	s_addc_u32 s47, s45, 0
	s_add_i32 s88, 0, 0x10000
	s_add_i32 s89, 0, 0x14000
	v_add_u32_e32 v62, s88, v184
	v_add_u32_e32 v160, s89, v184
	ds_read_b128 v[50:53], v62
	ds_read_b128 v[54:57], v62 offset:1024
	ds_read_b128 v[58:61], v62 offset:2048
	ds_read_b128 v[62:65], v62 offset:3072
	ds_read_b128 v[146:149], v160
	ds_read_b128 v[150:153], v160 offset:1024
	ds_read_b128 v[156:159], v160 offset:2048
	ds_read_b128 v[160:163], v160 offset:3072
	s_mul_hi_u32 s83, s82, 0x280000
	s_mul_i32 s82, s82, 0x280000
	s_add_u32 s82, s79, s82
	s_addc_u32 s83, s80, s83
	v_lshl_add_u64 v[206:207], s[82:83], 0, v[194:195]
	s_add_i32 m0, s68, 0xc000
	ds_read_b128 v[164:167], v185
	ds_read_b128 v[168:171], v185 offset:1024
	ds_read_b128 v[172:175], v185 offset:2048
	ds_read_b128 v[176:179], v185 offset:3072
	ds_read_b128 v[180:183], v185 offset:4096
	ds_read_b128 v[186:189], v185 offset:5120
	ds_read_b128 v[190:193], v185 offset:6144
	ds_read_b128 v[202:205], v185 offset:7168
	global_load_lds_dwordx4 v[206:207], off
	v_lshl_add_u64 v[206:207], s[82:83], 0, v[154:155]
	s_add_i32 m0, s68, 0xe000
	s_nop 0
	global_load_lds_dwordx4 v[206:207], off
	s_waitcnt vmcnt(8)
	s_waitcnt lgkmcnt(0)
	s_setprio 1
	s_barrier
	v_mfma_f32_16x16x32_bf16 v[142:145], v[50:53], v[164:167], v[142:145]
	v_mfma_f32_16x16x32_bf16 v[142:145], v[54:57], v[168:171], v[142:145]
	v_mfma_f32_16x16x32_bf16 v[126:129], v[54:57], v[176:179], v[126:129]
	v_mfma_f32_16x16x32_bf16 v[126:129], v[50:53], v[172:175], v[126:129]
	v_mfma_f32_16x16x32_bf16 v[110:113], v[50:53], v[180:183], v[110:113]
	v_mfma_f32_16x16x32_bf16 v[110:113], v[54:57], v[186:189], v[110:113]
	v_mfma_f32_16x16x32_bf16 v[94:97], v[54:57], v[202:205], v[94:97]
	v_mfma_f32_16x16x32_bf16 v[94:97], v[50:53], v[190:193], v[94:97]
	v_mfma_f32_16x16x32_bf16 v[90:93], v[58:61], v[190:193], v[90:93]
	v_mfma_f32_16x16x32_bf16 v[90:93], v[62:65], v[202:205], v[90:93]
	v_mfma_f32_16x16x32_bf16 v[106:109], v[62:65], v[186:189], v[106:109]
	v_mfma_f32_16x16x32_bf16 v[106:109], v[58:61], v[180:183], v[106:109]
	v_mfma_f32_16x16x32_bf16 v[122:125], v[58:61], v[172:175], v[122:125]
	v_mfma_f32_16x16x32_bf16 v[122:125], v[62:65], v[176:179], v[122:125]
	v_mfma_f32_16x16x32_bf16 v[138:141], v[62:65], v[168:171], v[138:141]
	v_mfma_f32_16x16x32_bf16 v[138:141], v[58:61], v[164:167], v[138:141]
	v_mfma_f32_16x16x32_bf16 v[134:137], v[146:149], v[164:167], v[134:137]
	v_mfma_f32_16x16x32_bf16 v[134:137], v[150:153], v[168:171], v[134:137]
	v_mfma_f32_16x16x32_bf16 v[118:121], v[150:153], v[176:179], v[118:121]
	v_mfma_f32_16x16x32_bf16 v[118:121], v[146:149], v[172:175], v[118:121]
	v_mfma_f32_16x16x32_bf16 v[102:105], v[146:149], v[180:183], v[102:105]
	v_mfma_f32_16x16x32_bf16 v[102:105], v[150:153], v[186:189], v[102:105]
	v_mfma_f32_16x16x32_bf16 v[86:89], v[150:153], v[202:205], v[86:89]
	v_mfma_f32_16x16x32_bf16 v[86:89], v[146:149], v[190:193], v[86:89]
	v_mfma_f32_16x16x32_bf16 v[82:85], v[156:159], v[190:193], v[82:85]
	v_mfma_f32_16x16x32_bf16 v[82:85], v[160:163], v[202:205], v[82:85]
	v_mfma_f32_16x16x32_bf16 v[98:101], v[160:163], v[186:189], v[98:101]
	v_mfma_f32_16x16x32_bf16 v[98:101], v[156:159], v[180:183], v[98:101]
	v_mfma_f32_16x16x32_bf16 v[114:117], v[156:159], v[172:175], v[114:117]
	v_mfma_f32_16x16x32_bf16 v[114:117], v[160:163], v[176:179], v[114:117]
	v_mfma_f32_16x16x32_bf16 v[130:133], v[160:163], v[168:171], v[130:133]
	v_mfma_f32_16x16x32_bf16 v[130:133], v[156:159], v[164:167], v[130:133]
	s_barrier
	s_setprio 0
	s_add_i32 s82, s88, s67
	v_lshl_add_u64 v[206:207], vcc, 0, v[194:195]
	s_mov_b32 m0, s82
	ds_read_b128 v[164:167], v185 offset:16384
	ds_read_b128 v[168:171], v185 offset:17408
	ds_read_b128 v[172:175], v185 offset:18432
	ds_read_b128 v[176:179], v185 offset:19456
	ds_read_b128 v[180:183], v185 offset:20480
	ds_read_b128 v[186:189], v185 offset:21504
	ds_read_b128 v[190:193], v185 offset:22528
	ds_read_b128 v[202:205], v185 offset:23552
	global_load_lds_dwordx4 v[206:207], off
	s_add_i32 m0, s82, 0x2000
	s_add_u32 s82, vcc_lo, 0x4000
	v_lshl_add_u64 v[206:207], vcc, 0, v[154:155]
	s_addc_u32 s83, vcc_hi, 0
	s_add_i32 s88, s89, s67
	global_load_lds_dwordx4 v[206:207], off
	v_lshl_add_u64 v[206:207], s[82:83], 0, v[194:195]
	s_mov_b32 m0, s88
	s_nop 0
	global_load_lds_dwordx4 v[206:207], off
	v_lshl_add_u64 v[206:207], s[82:83], 0, v[154:155]
	s_add_i32 m0, s88, 0x2000
	s_nop 0
	global_load_lds_dwordx4 v[206:207], off
	v_lshl_add_u64 v[206:207], s[44:45], 0, v[194:195]
	s_mov_b32 m0, s68
	s_nop 0
	global_load_lds_dwordx4 v[206:207], off
	v_lshl_add_u64 v[206:207], s[44:45], 0, v[154:155]
	s_mov_b32 m0, s69
	s_nop 0
	global_load_lds_dwordx4 v[206:207], off
	s_waitcnt vmcnt(8)
	s_waitcnt lgkmcnt(0)
	s_setprio 1
	s_barrier
	v_mfma_f32_16x16x32_bf16 v[78:81], v[50:53], v[164:167], v[78:81]
	v_mfma_f32_16x16x32_bf16 v[78:81], v[54:57], v[168:171], v[78:81]
	v_mfma_f32_16x16x32_bf16 v[46:49], v[54:57], v[176:179], v[46:49]
	v_mfma_f32_16x16x32_bf16 v[46:49], v[50:53], v[172:175], v[46:49]
	v_mfma_f32_16x16x32_bf16 v[30:33], v[50:53], v[180:183], v[30:33]
	v_mfma_f32_16x16x32_bf16 v[30:33], v[54:57], v[186:189], v[30:33]
	v_mfma_f32_16x16x32_bf16 v[14:17], v[54:57], v[202:205], v[14:17]
	v_mfma_f32_16x16x32_bf16 v[14:17], v[50:53], v[190:193], v[14:17]
	v_mfma_f32_16x16x32_bf16 v[10:13], v[58:61], v[190:193], v[10:13]
	v_mfma_f32_16x16x32_bf16 v[10:13], v[62:65], v[202:205], v[10:13]
	v_mfma_f32_16x16x32_bf16 v[26:29], v[62:65], v[186:189], v[26:29]
	v_mfma_f32_16x16x32_bf16 v[26:29], v[58:61], v[180:183], v[26:29]
	v_mfma_f32_16x16x32_bf16 v[42:45], v[58:61], v[172:175], v[42:45]
	v_mfma_f32_16x16x32_bf16 v[42:45], v[62:65], v[176:179], v[42:45]
	v_mfma_f32_16x16x32_bf16 v[74:77], v[62:65], v[168:171], v[74:77]
	v_mfma_f32_16x16x32_bf16 v[74:77], v[58:61], v[164:167], v[74:77]
	v_mfma_f32_16x16x32_bf16 v[38:41], v[146:149], v[172:175], v[38:41]
	v_mfma_f32_16x16x32_bf16 v[34:37], v[156:159], v[172:175], v[34:37]
	v_mfma_f32_16x16x32_bf16 v[22:25], v[146:149], v[180:183], v[22:25]
	v_mfma_f32_16x16x32_bf16 v[18:21], v[156:159], v[180:183], v[18:21]
	v_mfma_f32_16x16x32_bf16 v[6:9], v[146:149], v[190:193], v[6:9]
	v_mfma_f32_16x16x32_bf16 v[2:5], v[156:159], v[190:193], v[2:5]
	v_mfma_f32_16x16x32_bf16 v[50:53], v[146:149], v[164:167], v[70:73]
	v_mfma_f32_16x16x32_bf16 v[54:57], v[156:159], v[164:167], v[66:69]
	v_mfma_f32_16x16x32_bf16 v[38:41], v[150:153], v[176:179], v[38:41]
	v_mfma_f32_16x16x32_bf16 v[34:37], v[160:163], v[176:179], v[34:37]
	v_mfma_f32_16x16x32_bf16 v[22:25], v[150:153], v[186:189], v[22:25]
	v_mfma_f32_16x16x32_bf16 v[18:21], v[160:163], v[186:189], v[18:21]
	v_mfma_f32_16x16x32_bf16 v[6:9], v[150:153], v[202:205], v[6:9]
	v_mfma_f32_16x16x32_bf16 v[2:5], v[160:163], v[202:205], v[2:5]
	v_mfma_f32_16x16x32_bf16 v[50:53], v[150:153], v[168:171], v[50:53]
	v_mfma_f32_16x16x32_bf16 v[54:57], v[160:163], v[168:171], v[54:57]
	s_barrier
	s_setprio 0
	s_add_i32 s82, 0, 0x18000
	s_add_i32 s83, 0, 0x1c000
	v_add_u32_e32 v70, s82, v184
	v_add_u32_e32 v160, s83, v184
	ds_read_b128 v[58:61], v70
	ds_read_b128 v[62:65], v70 offset:1024
	ds_read_b128 v[66:69], v70 offset:2048
	ds_read_b128 v[70:73], v70 offset:3072
	ds_read_b128 v[146:149], v160
	ds_read_b128 v[150:153], v160 offset:1024
	ds_read_b128 v[156:159], v160 offset:2048
	ds_read_b128 v[160:163], v160 offset:3072
	s_add_u32 s44, s44, 0x4000
	s_addc_u32 s45, s45, 0
	s_mov_b32 m0, s72
	v_lshl_add_u64 v[206:207], s[44:45], 0, v[194:195]
	ds_read_b128 v[164:167], v185 offset:32768
	ds_read_b128 v[168:171], v185 offset:33792
	ds_read_b128 v[172:175], v185 offset:34816
	ds_read_b128 v[176:179], v185 offset:35840
	ds_read_b128 v[180:183], v185 offset:36864
	ds_read_b128 v[186:189], v185 offset:37888
	ds_read_b128 v[190:193], v185 offset:38912
	ds_read_b128 v[202:205], v185 offset:39936
	global_load_lds_dwordx4 v[206:207], off
	v_lshl_add_u64 v[206:207], s[44:45], 0, v[154:155]
	s_mov_b32 m0, s73
	s_nop 0
	global_load_lds_dwordx4 v[206:207], off
	s_waitcnt vmcnt(8)
	s_waitcnt lgkmcnt(0)
	s_setprio 1
	s_barrier
	v_mfma_f32_16x16x32_bf16 v[142:145], v[58:61], v[164:167], v[142:145]
	v_mfma_f32_16x16x32_bf16 v[142:145], v[62:65], v[168:171], v[142:145]
	v_mfma_f32_16x16x32_bf16 v[126:129], v[62:65], v[176:179], v[126:129]
	v_mfma_f32_16x16x32_bf16 v[126:129], v[58:61], v[172:175], v[126:129]
	v_mfma_f32_16x16x32_bf16 v[110:113], v[58:61], v[180:183], v[110:113]
	v_mfma_f32_16x16x32_bf16 v[110:113], v[62:65], v[186:189], v[110:113]
	v_mfma_f32_16x16x32_bf16 v[94:97], v[62:65], v[202:205], v[94:97]
	v_mfma_f32_16x16x32_bf16 v[94:97], v[58:61], v[190:193], v[94:97]
	v_mfma_f32_16x16x32_bf16 v[90:93], v[66:69], v[190:193], v[90:93]
	v_mfma_f32_16x16x32_bf16 v[90:93], v[70:73], v[202:205], v[90:93]
	v_mfma_f32_16x16x32_bf16 v[106:109], v[70:73], v[186:189], v[106:109]
	v_mfma_f32_16x16x32_bf16 v[106:109], v[66:69], v[180:183], v[106:109]
	v_mfma_f32_16x16x32_bf16 v[122:125], v[66:69], v[172:175], v[122:125]
	v_mfma_f32_16x16x32_bf16 v[122:125], v[70:73], v[176:179], v[122:125]
	v_mfma_f32_16x16x32_bf16 v[138:141], v[70:73], v[168:171], v[138:141]
	v_mfma_f32_16x16x32_bf16 v[138:141], v[66:69], v[164:167], v[138:141]
	v_mfma_f32_16x16x32_bf16 v[134:137], v[146:149], v[164:167], v[134:137]
	v_mfma_f32_16x16x32_bf16 v[134:137], v[150:153], v[168:171], v[134:137]
	v_mfma_f32_16x16x32_bf16 v[118:121], v[150:153], v[176:179], v[118:121]
	v_mfma_f32_16x16x32_bf16 v[118:121], v[146:149], v[172:175], v[118:121]
	v_mfma_f32_16x16x32_bf16 v[102:105], v[146:149], v[180:183], v[102:105]
	v_mfma_f32_16x16x32_bf16 v[102:105], v[150:153], v[186:189], v[102:105]
	v_mfma_f32_16x16x32_bf16 v[86:89], v[150:153], v[202:205], v[86:89]
	v_mfma_f32_16x16x32_bf16 v[86:89], v[146:149], v[190:193], v[86:89]
	v_mfma_f32_16x16x32_bf16 v[82:85], v[156:159], v[190:193], v[82:85]
	v_mfma_f32_16x16x32_bf16 v[82:85], v[160:163], v[202:205], v[82:85]
	v_mfma_f32_16x16x32_bf16 v[98:101], v[160:163], v[186:189], v[98:101]
	v_mfma_f32_16x16x32_bf16 v[98:101], v[156:159], v[180:183], v[98:101]
	v_mfma_f32_16x16x32_bf16 v[114:117], v[156:159], v[172:175], v[114:117]
	v_mfma_f32_16x16x32_bf16 v[114:117], v[160:163], v[176:179], v[114:117]
	v_mfma_f32_16x16x32_bf16 v[130:133], v[160:163], v[168:171], v[130:133]
	v_mfma_f32_16x16x32_bf16 v[130:133], v[156:159], v[164:167], v[130:133]
	s_barrier
	s_setprio 0
	s_add_u32 s44, vcc_lo, 0x40000
	s_addc_u32 s45, vcc_hi, 0
	s_add_i32 s82, s82, s67
	v_lshl_add_u64 v[206:207], s[44:45], 0, v[194:195]
	s_mov_b32 m0, s82
	ds_read_b128 v[164:167], v185 offset:49152
	ds_read_b128 v[168:171], v185 offset:50176
	ds_read_b128 v[172:175], v185 offset:51200
	ds_read_b128 v[176:179], v185 offset:52224
	ds_read_b128 v[180:183], v185 offset:53248
	ds_read_b128 v[186:189], v185 offset:54272
	ds_read_b128 v[190:193], v185 offset:55296
	ds_read_b128 v[202:205], v185 offset:56320
	global_load_lds_dwordx4 v[206:207], off
	s_add_i32 m0, s82, 0x2000
	v_lshl_add_u64 v[206:207], s[44:45], 0, v[154:155]
	s_add_u32 s44, vcc_lo, 0x44000
	s_addc_u32 s45, vcc_hi, 0
	s_add_i32 s82, s83, s67
	global_load_lds_dwordx4 v[206:207], off
	v_lshl_add_u64 v[206:207], s[44:45], 0, v[194:195]
	s_mov_b32 m0, s82
	s_nop 0
	global_load_lds_dwordx4 v[206:207], off
	v_lshl_add_u64 v[206:207], s[44:45], 0, v[154:155]
	s_add_i32 m0, s82, 0x2000
	s_nop 0
	global_load_lds_dwordx4 v[206:207], off
	v_lshl_add_u64 v[206:207], s[46:47], 0, v[194:195]
	s_mov_b32 m0, s76
	s_nop 0
	global_load_lds_dwordx4 v[206:207], off
	v_lshl_add_u64 v[206:207], s[46:47], 0, v[154:155]
	s_mov_b32 m0, s77
	s_nop 0
	global_load_lds_dwordx4 v[206:207], off
	s_waitcnt vmcnt(8)
	s_waitcnt lgkmcnt(0)
	s_setprio 1
	s_barrier
	v_mfma_f32_16x16x32_bf16 v[78:81], v[58:61], v[164:167], v[78:81]
	v_mfma_f32_16x16x32_bf16 v[78:81], v[62:65], v[168:171], v[78:81]
	v_mfma_f32_16x16x32_bf16 v[46:49], v[62:65], v[176:179], v[46:49]
	v_mfma_f32_16x16x32_bf16 v[46:49], v[58:61], v[172:175], v[46:49]
	v_mfma_f32_16x16x32_bf16 v[30:33], v[58:61], v[180:183], v[30:33]
	v_mfma_f32_16x16x32_bf16 v[30:33], v[62:65], v[186:189], v[30:33]
	v_mfma_f32_16x16x32_bf16 v[14:17], v[62:65], v[202:205], v[14:17]
	v_mfma_f32_16x16x32_bf16 v[14:17], v[58:61], v[190:193], v[14:17]
	v_mfma_f32_16x16x32_bf16 v[10:13], v[66:69], v[190:193], v[10:13]
	v_mfma_f32_16x16x32_bf16 v[10:13], v[70:73], v[202:205], v[10:13]
	v_mfma_f32_16x16x32_bf16 v[26:29], v[70:73], v[186:189], v[26:29]
	v_mfma_f32_16x16x32_bf16 v[26:29], v[66:69], v[180:183], v[26:29]
	v_mfma_f32_16x16x32_bf16 v[42:45], v[66:69], v[172:175], v[42:45]
	v_mfma_f32_16x16x32_bf16 v[42:45], v[70:73], v[176:179], v[42:45]
	v_mfma_f32_16x16x32_bf16 v[74:77], v[70:73], v[168:171], v[74:77]
	v_mfma_f32_16x16x32_bf16 v[74:77], v[66:69], v[164:167], v[74:77]
	v_mfma_f32_16x16x32_bf16 v[50:53], v[146:149], v[164:167], v[50:53]
	v_mfma_f32_16x16x32_bf16 v[70:73], v[150:153], v[168:171], v[50:53]
	v_mfma_f32_16x16x32_bf16 v[50:53], v[156:159], v[164:167], v[54:57]
	v_mfma_f32_16x16x32_bf16 v[38:41], v[146:149], v[172:175], v[38:41]
	v_mfma_f32_16x16x32_bf16 v[34:37], v[156:159], v[172:175], v[34:37]
	v_mfma_f32_16x16x32_bf16 v[22:25], v[146:149], v[180:183], v[22:25]
	v_mfma_f32_16x16x32_bf16 v[18:21], v[156:159], v[180:183], v[18:21]
	v_mfma_f32_16x16x32_bf16 v[6:9], v[146:149], v[190:193], v[6:9]
	v_mfma_f32_16x16x32_bf16 v[2:5], v[156:159], v[190:193], v[2:5]
	v_mfma_f32_16x16x32_bf16 v[66:69], v[160:163], v[168:171], v[50:53]
	v_mfma_f32_16x16x32_bf16 v[38:41], v[150:153], v[176:179], v[38:41]
	v_mfma_f32_16x16x32_bf16 v[34:37], v[160:163], v[176:179], v[34:37]
	v_mfma_f32_16x16x32_bf16 v[22:25], v[150:153], v[186:189], v[22:25]
	v_mfma_f32_16x16x32_bf16 v[18:21], v[160:163], v[186:189], v[18:21]
	v_mfma_f32_16x16x32_bf16 v[6:9], v[150:153], v[202:205], v[6:9]
	v_mfma_f32_16x16x32_bf16 v[2:5], v[160:163], v[202:205], v[2:5]
	s_barrier
	s_setprio 0
	s_cmpk_gt_u32 s81, 0x7d
	s_mov_b32 s81, s4
	s_cbranch_scc1 .LBB0_1505
